# v60 + sc1x:kabl0 (sc1 write-through hint also on plain stores of P0/KT/P2a/P2b/LN1)
# baseline (speedup 1.0000x reference)
.LBB0_129:
	s_or_b64 exec, exec, s[8:9]
	v_readlane_b32 s2, v254, 15
	v_ashrrev_i32_e32 v19, 31, v18
	v_mov_b32_e32 v13, 0x73
	v_readlane_b32 s3, v254, 16
	v_mad_i64_i32 v[26:27], s[2:3], s2, v13, v[18:19]
	s_movk_i32 s4, 0x50
	s_waitcnt lgkmcnt(0)
	v_mov_b64_e32 v[28:29], s[58:59]
	v_mad_u64_u32 v[28:29], s[2:3], v26, s4, v[28:29]
	v_mad_i32_i24 v29, v27, s4, v29
	s_mov_b64 s[2:3], 0x100000
	v_lshl_add_u64 v[26:27], v[28:29], 0, s[2:3]
	s_mov_b32 s2, 0x100000
	v_add_co_u32_e32 v28, vcc, s2, v28
	v_mov_b32_e32 v14, v17
	s_nop 0
	v_addc_co_u32_e32 v29, vcc, 0, v29, vcc
	v_mov_b32_e32 v16, v20
	global_store_dwordx4 v[28:29], v[4:7], off sc1
	global_store_dwordx4 v[26:27], v[8:11], off offset:16 sc1
	global_store_dwordx2 v[26:27], v[22:23], off offset:32 sc1
	global_store_dwordx4 v[26:27], v[0:3], off offset:40 sc1
	global_store_dwordx3 v[26:27], v[14:16], off offset:56 sc1
	v_mov_b32_e32 v13, v12
	s_nop 0
	v_mov_b32_e32 v14, v12
	global_store_dwordx3 v[26:27], v[12:14], off offset:68 sc1

.LBB0_162:
	s_or_b64 exec, exec, s[36:37]
	v_mov_b32_e32 v40, 0
	s_waitcnt vmcnt(0)
	v_cvt_pk_fp8_f32 v40, v12, v13
	v_cvt_pk_bf16_f32 v12, v12, v13
	v_cvt_pk_bf16_f32 v13, v14, v15
	v_cvt_pk_fp8_f32 v40, v14, v15 op_sel:[0,0,1]
	v_lshl_add_u64 v[14:15], s[58:59], 0, v[26:27]
	global_store_dwordx2 v[14:15], v[12:13], off sc1
	v_lshl_add_u64 v[12:13], s[58:59], 0, v[22:23]
	global_store_dword v[12:13], v40, off sc1
	s_and_saveexec_b64 s[36:37], vcc
	s_cbranch_execz .LBB0_165
	v_mov_b32_e32 v40, 0
	v_cvt_pk_fp8_f32 v40, v0, v1
	v_cvt_pk_bf16_f32 v12, v0, v1
	v_cvt_pk_bf16_f32 v13, v2, v3
	v_lshl_add_u64 v[14:15], s[58:59], 0, v[24:25]
	v_cvt_pk_fp8_f32 v40, v2, v3 op_sel:[0,0,1]
	global_store_dwordx2 v[14:15], v[12:13], off sc1
	v_lshl_add_u64 v[12:13], s[58:59], 0, v[20:21]
	global_store_dword v[12:13], v40, off sc1
	s_or_b64 exec, exec, s[36:37]
	s_and_saveexec_b64 s[36:37], s[4:5]
	s_cbranch_execnz .LBB0_166

.LBB0_166:
	v_mov_b32_e32 v40, 0
	v_cvt_pk_fp8_f32 v40, v4, v5
	v_cvt_pk_bf16_f32 v12, v4, v5
	v_cvt_pk_bf16_f32 v13, v6, v7
	v_lshl_add_u64 v[14:15], s[58:59], 0, v[32:33]
	v_cvt_pk_fp8_f32 v40, v6, v7 op_sel:[0,0,1]
	global_store_dwordx2 v[14:15], v[12:13], off sc1
	v_lshl_add_u64 v[12:13], s[58:59], 0, v[30:31]
	global_store_dword v[12:13], v40, off sc1
	s_or_b64 exec, exec, s[36:37]
	s_and_saveexec_b64 s[4:5], s[6:7]
	s_cbranch_execz .LBB0_155
.LBB0_167:
	v_mov_b32_e32 v40, 0
	v_cvt_pk_fp8_f32 v40, v8, v9
	v_cvt_pk_bf16_f32 v12, v8, v9
	v_cvt_pk_bf16_f32 v13, v10, v11
	v_lshl_add_u64 v[14:15], s[58:59], 0, v[36:37]
	v_cvt_pk_fp8_f32 v40, v10, v11 op_sel:[0,0,1]
	global_store_dwordx2 v[14:15], v[12:13], off sc1
	v_lshl_add_u64 v[12:13], s[58:59], 0, v[34:35]
	global_store_dword v[12:13], v40, off sc1
	s_branch .LBB0_155

.LBB0_170:
	global_load_dwordx4 v[4:7], v[2:3], off offset:-16
	global_load_dwordx4 v[8:11], v[2:3], off
	v_lshl_add_u64 v[16:17], v[16:17], 0, s[8:9]
	v_cmp_lt_u64_e32 vcc, s[14:15], v[16:17]
	v_lshl_add_u64 v[2:3], v[2:3], 0, s[10:11]
	s_or_b64 s[12:13], vcc, s[12:13]
	s_waitcnt vmcnt(1)
	v_cvt_pk_bf16_f32 v4, v4, v5
	v_cvt_pk_bf16_f32 v5, v6, v7
	s_waitcnt vmcnt(0)
	v_cvt_pk_bf16_f32 v6, v8, v9
	v_cvt_pk_bf16_f32 v7, v10, v11
	global_store_dwordx4 v[0:1], v[4:7], off sc1
	v_lshl_add_u64 v[0:1], v[0:1], 0, s[6:7]
	s_andn2_b64 exec, exec, s[12:13]
	s_cbranch_execnz .LBB0_170

.LBB0_382:
	s_and_b32 s0, s2, 31
	s_and_b32 s6, s8, 0xffffffc0
	s_and_b32 s10, s2, 28
	s_getpc_b64 s[4:5]
	s_add_u32 s4, s4, _ZL5LOG2G@rel32@lo+4
	s_addc_u32 s5, s5, _ZL5LOG2G@rel32@hi+12
	s_and_b32 s7, s8, 64
	v_add_u32_e32 v30, s6, v4
	s_lshl_b32 s11, s0, 6
	s_lshl_b32 s0, s0, 7
	v_add_u32_e32 v32, s6, v8
	v_add_u32_e32 v34, s6, v9
	v_add_u32_e32 v36, s6, v10
	v_add_u32_e32 v38, s6, v11
	v_add_u32_e32 v40, s6, v12
	v_add_u32_e32 v42, s6, v13
	v_add_u32_e32 v44, s6, v6
	v_or_b32_e32 v48, s7, v5
	v_bitop3_b32 v49, s7, v29, v5 bitop3:0x36
	v_ashrrev_i32_e32 v31, 31, v30
	v_lshl_add_u64 v[46:47], v[0:1], 0, s[0:1]
	v_ashrrev_i32_e32 v33, 31, v32
	v_ashrrev_i32_e32 v35, 31, v34
	v_ashrrev_i32_e32 v37, 31, v36
	v_ashrrev_i32_e32 v39, 31, v38
	v_ashrrev_i32_e32 v41, 31, v40
	v_ashrrev_i32_e32 v43, 31, v42
	v_ashrrev_i32_e32 v45, 31, v44
	v_cvt_f32_ubyte0_e32 v94, v49
	v_sub_u32_e32 v49, 0x7e, v48
	v_sub_u32_e32 v51, 0x7d, v48
	v_sub_u32_e32 v53, 0x7c, v48
	v_sub_u32_e32 v55, 0x7b, v48
	v_sub_u32_e32 v57, 0x7a, v48
	v_sub_u32_e32 v59, 0x79, v48
	v_sub_u32_e32 v61, 0x78, v48
	v_add_u32_e32 v48, s11, v4
	v_add_u32_e32 v50, s11, v8
	v_add_u32_e32 v52, s11, v9
	v_add_u32_e32 v54, s11, v10
	v_add_u32_e32 v56, s11, v11
	v_add_u32_e32 v58, s11, v12
	v_add_u32_e32 v60, s11, v13
	v_lshlrev_b64 v[30:31], 12, v[30:31]
	v_lshlrev_b64 v[32:33], 12, v[32:33]
	v_lshlrev_b64 v[34:35], 12, v[34:35]
	v_lshlrev_b64 v[36:37], 12, v[36:37]
	v_lshlrev_b64 v[38:39], 12, v[38:39]
	v_lshlrev_b64 v[40:41], 12, v[40:41]
	v_lshlrev_b64 v[42:43], 12, v[42:43]
	v_lshlrev_b64 v[44:45], 12, v[44:45]
	v_cvt_f32_ubyte0_e32 v95, v49
	v_cvt_f32_ubyte0_e32 v96, v51
	v_cvt_f32_ubyte0_e32 v97, v53
	v_cvt_f32_ubyte0_e32 v98, v55
	v_cvt_f32_ubyte0_e32 v99, v57
	v_cvt_f32_ubyte0_e32 v100, v59
	v_cvt_f32_ubyte0_e32 v101, v61
	v_ashrrev_i32_e32 v49, 31, v48
	v_ashrrev_i32_e32 v51, 31, v50
	v_ashrrev_i32_e32 v53, 31, v52
	v_ashrrev_i32_e32 v55, 31, v54
	v_ashrrev_i32_e32 v57, 31, v56
	v_ashrrev_i32_e32 v59, 31, v58
	v_ashrrev_i32_e32 v61, 31, v60
	v_lshl_add_u64 v[30:31], v[46:47], 0, v[30:31]
	v_lshl_add_u64 v[66:67], v[46:47], 0, v[32:33]
	v_lshl_add_u64 v[68:69], v[46:47], 0, v[34:35]
	v_lshl_add_u64 v[70:71], v[46:47], 0, v[36:37]
	v_lshl_add_u64 v[72:73], v[46:47], 0, v[38:39]
	v_lshl_add_u64 v[74:75], v[46:47], 0, v[40:41]
	v_lshl_add_u64 v[76:77], v[46:47], 0, v[42:43]
	v_lshl_add_u64 v[78:79], v[46:47], 0, v[44:45]
	v_lshlrev_b64 v[80:81], 15, v[48:49]
	v_lshlrev_b64 v[82:83], 15, v[50:51]
	v_lshlrev_b64 v[84:85], 15, v[52:53]
	v_lshlrev_b64 v[86:87], 15, v[54:55]
	v_lshlrev_b64 v[88:89], 15, v[56:57]
	v_lshlrev_b64 v[90:91], 15, v[58:59]
	v_lshlrev_b64 v[92:93], 15, v[60:61]
	global_load_dwordx4 v[30:33], v[30:31], off nt
	s_nop 0
	global_load_dwordx4 v[34:37], v[66:67], off nt
	global_load_dwordx4 v[38:41], v[68:69], off nt
	global_load_dwordx4 v[42:45], v[70:71], off nt
	global_load_dwordx4 v[46:49], v[72:73], off nt
	global_load_dwordx4 v[50:53], v[74:75], off nt
	global_load_dwordx4 v[54:57], v[76:77], off nt
	global_load_dwordx4 v[58:61], v[78:79], off nt
	v_add_u32_e32 v64, s11, v6
	s_ashr_i32 s7, s6, 31
	v_ashrrev_i32_e32 v65, 31, v64
	v_lshl_add_u64 v[62:63], s[6:7], 1, v[2:3]
	v_lshlrev_b64 v[64:65], 15, v[64:65]
	v_lshl_add_u64 v[66:67], v[62:63], 0, v[80:81]
	v_lshl_add_u64 v[68:69], v[62:63], 0, v[82:83]
	s_waitcnt vmcnt(7)
	ds_write2_b32 v14, v30, v31 offset1:1
	ds_write2_b32 v14, v32, v33 offset0:2 offset1:3
	s_waitcnt vmcnt(6)
	ds_write2_b32 v15, v34, v35 offset1:1
	ds_write2_b32 v16, v36, v37 offset1:1
	s_waitcnt vmcnt(5)
	ds_write2_b32 v17, v38, v39 offset1:1
	ds_write2_b32 v18, v40, v41 offset1:1
	s_waitcnt vmcnt(4)
	ds_write2_b32 v19, v42, v43 offset1:1
	ds_write2_b32 v20, v44, v45 offset1:1
	s_waitcnt vmcnt(3)
	ds_write2_b32 v21, v46, v47 offset1:1
	ds_write2_b32 v22, v48, v49 offset1:1
	s_waitcnt vmcnt(2)
	ds_write2_b32 v23, v50, v51 offset1:1
	ds_write2_b32 v24, v52, v53 offset1:1
	s_waitcnt vmcnt(1)
	ds_write2_b32 v25, v54, v55 offset1:1
	ds_write2_b32 v26, v56, v57 offset1:1
	s_waitcnt vmcnt(0)
	ds_write2_b32 v27, v58, v59 offset1:1
	ds_write2_b32 v28, v60, v61 offset1:1
	s_waitcnt lgkmcnt(0)
	s_load_dword s0, s[4:5], s10 offset:0x0
	v_lshl_add_u64 v[70:71], v[62:63], 0, v[84:85]
	v_lshl_add_u64 v[72:73], v[62:63], 0, v[86:87]
	v_lshl_add_u64 v[74:75], v[62:63], 0, v[88:89]
	v_lshl_add_u64 v[76:77], v[62:63], 0, v[90:91]
	v_lshl_add_u64 v[78:79], v[62:63], 0, v[92:93]
	v_lshl_add_u64 v[62:63], v[62:63], 0, v[64:65]
	ds_read_u16 v30, v7
	ds_read_u16 v38, v7 offset:16
	ds_read_u16 v46, v7 offset:32
	ds_read_u16 v54, v7 offset:48
	ds_read_u16 v64, v7 offset:64
	ds_read_u16 v86, v7 offset:80
	ds_read_u16 v102, v7 offset:96
	ds_read_u16 v104, v7 offset:112
	ds_read_u16 v31, v7 offset:132
	ds_read_u16 v39, v7 offset:148
	ds_read_u16 v47, v7 offset:164
	ds_read_u16 v55, v7 offset:180
	ds_read_u16 v65, v7 offset:196
	ds_read_u16 v87, v7 offset:212
	ds_read_u16 v103, v7 offset:228
	ds_read_u16 v105, v7 offset:244
	ds_read_u16 v32, v7 offset:264
	ds_read_u16 v40, v7 offset:280
	ds_read_u16 v48, v7 offset:296
	ds_read_u16 v56, v7 offset:312
	ds_read_u16 v80, v7 offset:328
	ds_read_u16 v88, v7 offset:344
	ds_read_u16 v106, v7 offset:360
	ds_read_u16 v107, v7 offset:376
	ds_read_u16 v33, v7 offset:396
	ds_read_u16 v41, v7 offset:412
	ds_read_u16 v49, v7 offset:428
	ds_read_u16 v57, v7 offset:444
	ds_read_u16 v81, v7 offset:460
	ds_read_u16 v89, v7 offset:476
	ds_read_u16 v108, v7 offset:492
	ds_read_u16 v109, v7 offset:508
	ds_read_u16 v34, v7 offset:528
	ds_read_u16 v42, v7 offset:544
	ds_read_u16 v50, v7 offset:560
	ds_read_u16 v58, v7 offset:576
	ds_read_u16 v82, v7 offset:592
	ds_read_u16 v90, v7 offset:608
	ds_read_u16 v110, v7 offset:624
	ds_read_u16 v111, v7 offset:640
	ds_read_u16 v35, v7 offset:660
	ds_read_u16 v43, v7 offset:676
	ds_read_u16 v51, v7 offset:692
	ds_read_u16 v59, v7 offset:708
	ds_read_u16 v83, v7 offset:724
	ds_read_u16 v91, v7 offset:740
	ds_read_u16 v112, v7 offset:756
	ds_read_u16 v113, v7 offset:772
	ds_read_u16 v36, v7 offset:792
	ds_read_u16 v44, v7 offset:808
	ds_read_u16 v52, v7 offset:824
	ds_read_u16 v60, v7 offset:840
	ds_read_u16 v84, v7 offset:856
	ds_read_u16 v92, v7 offset:872
	ds_read_u16 v114, v7 offset:888
	ds_read_u16 v115, v7 offset:904
	ds_read_u16 v37, v7 offset:924
	ds_read_u16 v45, v7 offset:940
	ds_read_u16 v53, v7 offset:956
	ds_read_u16 v61, v7 offset:972
	ds_read_u16 v85, v7 offset:988
	ds_read_u16 v93, v7 offset:1004
	ds_read_u16 v116, v7 offset:1020
	ds_read_u16 v117, v7 offset:1036
	s_waitcnt lgkmcnt(0)
	v_mul_f32_e32 v118, s0, v94
	v_mul_f32_e32 v119, s0, v95
	v_mul_f32_e32 v120, s0, v96
	v_mul_f32_e32 v121, s0, v97
	v_mul_f32_e32 v122, s0, v98
	v_mul_f32_e32 v123, s0, v99
	v_mul_f32_e32 v124, s0, v100
	v_mul_f32_e32 v125, s0, v101
	v_lshlrev_b32_e32 v95, 16, v103
	v_lshlrev_b32_e32 v94, 16, v102
	v_lshlrev_b32_e32 v97, 16, v108
	v_lshlrev_b32_e32 v96, 16, v106
	v_lshlrev_b32_e32 v99, 16, v112
	v_lshlrev_b32_e32 v98, 16, v110
	v_lshlrev_b32_e32 v101, 16, v116
	v_lshlrev_b32_e32 v100, 16, v114
	v_lshlrev_b32_e32 v103, 16, v105
	v_lshlrev_b32_e32 v102, 16, v104
	v_lshlrev_b32_e32 v105, 16, v109
	v_lshlrev_b32_e32 v104, 16, v107
	v_lshlrev_b32_e32 v107, 16, v113
	v_lshlrev_b32_e32 v106, 16, v111
	v_lshlrev_b32_e32 v109, 16, v117
	v_lshlrev_b32_e32 v108, 16, v115
	v_exp_f32_e32 v110, v118
	v_exp_f32_e32 v111, v119
	v_exp_f32_e32 v112, v120
	v_exp_f32_e32 v113, v121
	v_exp_f32_e32 v114, v122
	v_exp_f32_e32 v115, v123
	v_exp_f32_e32 v116, v124
	v_exp_f32_e32 v117, v125
	v_lshlrev_b32_e32 v31, 16, v31
	v_lshlrev_b32_e32 v30, 16, v30
	v_lshlrev_b32_e32 v33, 16, v33
	v_lshlrev_b32_e32 v32, 16, v32
	v_lshlrev_b32_e32 v35, 16, v35
	v_lshlrev_b32_e32 v34, 16, v34
	v_lshlrev_b32_e32 v37, 16, v37
	v_lshlrev_b32_e32 v36, 16, v36
	v_lshlrev_b32_e32 v39, 16, v39
	v_lshlrev_b32_e32 v38, 16, v38
	v_lshlrev_b32_e32 v41, 16, v41
	v_lshlrev_b32_e32 v40, 16, v40
	v_lshlrev_b32_e32 v43, 16, v43
	v_lshlrev_b32_e32 v42, 16, v42
	v_lshlrev_b32_e32 v45, 16, v45
	v_lshlrev_b32_e32 v44, 16, v44
	v_lshlrev_b32_e32 v47, 16, v47
	v_lshlrev_b32_e32 v46, 16, v46
	v_lshlrev_b32_e32 v49, 16, v49
	v_lshlrev_b32_e32 v48, 16, v48
	v_lshlrev_b32_e32 v51, 16, v51
	v_lshlrev_b32_e32 v50, 16, v50
	v_lshlrev_b32_e32 v53, 16, v53
	v_lshlrev_b32_e32 v52, 16, v52
	v_lshlrev_b32_e32 v55, 16, v55
	v_lshlrev_b32_e32 v54, 16, v54
	v_lshlrev_b32_e32 v57, 16, v57
	v_lshlrev_b32_e32 v56, 16, v56
	v_lshlrev_b32_e32 v59, 16, v59
	v_lshlrev_b32_e32 v58, 16, v58
	v_lshlrev_b32_e32 v61, 16, v61
	v_lshlrev_b32_e32 v60, 16, v60
	v_lshlrev_b32_e32 v65, 16, v65
	v_lshlrev_b32_e32 v64, 16, v64
	v_lshlrev_b32_e32 v81, 16, v81
	v_lshlrev_b32_e32 v80, 16, v80
	v_lshlrev_b32_e32 v83, 16, v83
	v_lshlrev_b32_e32 v82, 16, v82
	v_lshlrev_b32_e32 v85, 16, v85
	v_lshlrev_b32_e32 v84, 16, v84
	v_lshlrev_b32_e32 v87, 16, v87
	v_lshlrev_b32_e32 v86, 16, v86
	v_lshlrev_b32_e32 v89, 16, v89
	v_lshlrev_b32_e32 v88, 16, v88
	v_lshlrev_b32_e32 v91, 16, v91
	v_lshlrev_b32_e32 v90, 16, v90
	v_lshlrev_b32_e32 v93, 16, v93
	v_lshlrev_b32_e32 v92, 16, v92
	v_pk_mul_f32 v[30:31], v[110:111], v[30:31]
	v_pk_mul_f32 v[32:33], v[112:113], v[32:33]
	v_pk_mul_f32 v[34:35], v[114:115], v[34:35]
	v_pk_mul_f32 v[36:37], v[116:117], v[36:37]
	v_pk_mul_f32 v[38:39], v[110:111], v[38:39]
	v_pk_mul_f32 v[40:41], v[112:113], v[40:41]
	v_pk_mul_f32 v[42:43], v[114:115], v[42:43]
	v_pk_mul_f32 v[44:45], v[116:117], v[44:45]
	v_pk_mul_f32 v[46:47], v[110:111], v[46:47]
	v_pk_mul_f32 v[48:49], v[112:113], v[48:49]
	v_pk_mul_f32 v[50:51], v[114:115], v[50:51]
	v_pk_mul_f32 v[52:53], v[116:117], v[52:53]
	v_pk_mul_f32 v[54:55], v[110:111], v[54:55]
	v_pk_mul_f32 v[56:57], v[112:113], v[56:57]
	v_pk_mul_f32 v[58:59], v[114:115], v[58:59]
	v_pk_mul_f32 v[60:61], v[116:117], v[60:61]
	v_pk_mul_f32 v[64:65], v[110:111], v[64:65]
	v_pk_mul_f32 v[80:81], v[112:113], v[80:81]
	v_pk_mul_f32 v[82:83], v[114:115], v[82:83]
	v_pk_mul_f32 v[84:85], v[116:117], v[84:85]
	v_pk_mul_f32 v[86:87], v[110:111], v[86:87]
	v_pk_mul_f32 v[88:89], v[112:113], v[88:89]
	v_pk_mul_f32 v[90:91], v[114:115], v[90:91]
	v_pk_mul_f32 v[92:93], v[116:117], v[92:93]
	v_pk_mul_f32 v[94:95], v[110:111], v[94:95]
	v_pk_mul_f32 v[96:97], v[112:113], v[96:97]
	v_pk_mul_f32 v[98:99], v[114:115], v[98:99]
	v_pk_mul_f32 v[100:101], v[116:117], v[100:101]
	v_pk_mul_f32 v[102:103], v[110:111], v[102:103]
	v_pk_mul_f32 v[104:105], v[112:113], v[104:105]
	v_pk_mul_f32 v[106:107], v[114:115], v[106:107]
	v_pk_mul_f32 v[108:109], v[116:117], v[108:109]
	v_cvt_pk_bf16_f32 v30, v30, v31
	v_cvt_pk_bf16_f32 v31, v32, v33
	v_cvt_pk_bf16_f32 v32, v34, v35
	v_cvt_pk_bf16_f32 v33, v36, v37
	v_cvt_pk_bf16_f32 v34, v38, v39
	v_cvt_pk_bf16_f32 v35, v40, v41
	v_cvt_pk_bf16_f32 v36, v42, v43
	v_cvt_pk_bf16_f32 v37, v44, v45
	v_cvt_pk_bf16_f32 v38, v46, v47
	v_cvt_pk_bf16_f32 v39, v48, v49
	v_cvt_pk_bf16_f32 v40, v50, v51
	v_cvt_pk_bf16_f32 v41, v52, v53
	v_cvt_pk_bf16_f32 v42, v54, v55
	v_cvt_pk_bf16_f32 v43, v56, v57
	v_cvt_pk_bf16_f32 v44, v58, v59
	v_cvt_pk_bf16_f32 v45, v60, v61
	v_cvt_pk_bf16_f32 v46, v64, v65
	v_cvt_pk_bf16_f32 v47, v80, v81
	v_cvt_pk_bf16_f32 v48, v82, v83
	v_cvt_pk_bf16_f32 v49, v84, v85
	v_cvt_pk_bf16_f32 v50, v86, v87
	v_cvt_pk_bf16_f32 v51, v88, v89
	v_cvt_pk_bf16_f32 v52, v90, v91
	v_cvt_pk_bf16_f32 v53, v92, v93
	v_cvt_pk_bf16_f32 v54, v94, v95
	v_cvt_pk_bf16_f32 v55, v96, v97
	v_cvt_pk_bf16_f32 v56, v98, v99
	v_cvt_pk_bf16_f32 v57, v100, v101
	v_cvt_pk_bf16_f32 v58, v102, v103
	v_cvt_pk_bf16_f32 v59, v104, v105
	v_cvt_pk_bf16_f32 v60, v106, v107
	v_cvt_pk_bf16_f32 v61, v108, v109
	global_store_dwordx4 v[66:67], v[30:33], off sc1
	global_store_dwordx4 v[68:69], v[34:37], off sc1
	global_store_dwordx4 v[70:71], v[38:41], off sc1
	global_store_dwordx4 v[72:73], v[42:45], off sc1
	global_store_dwordx4 v[74:75], v[46:49], off sc1
	global_store_dwordx4 v[76:77], v[50:53], off sc1
	global_store_dwordx4 v[78:79], v[54:57], off sc1
	global_store_dwordx4 v[62:63], v[58:61], off sc1
	s_waitcnt lgkmcnt(0)
	s_add_i32 s2, s2, s3
	s_add_i32 s8, s8, s9
	s_cmpk_lt_i32 s2, 0x2000
	s_cbranch_scc1 .LBB0_382

.LBB0_455:
	v_mbcnt_lo_u32_b32 v80, -1, 0
	v_mbcnt_hi_u32_b32 v80, -1, v80
	s_nop 1
	v_and_b32_e32 v81, 15, v80
	v_ashrrev_i32_e32 v80, 1, v80
	v_add_u32_e32 v104, s53, v80
	v_bfe_u32 v107, v80, 3, 1
	v_ashrrev_i32_e32 v80, 3, v104
	v_or_b32_e32 v106, s52, v81
	v_and_b32_e32 v112, -2, v80
	v_or_b32_e32 v113, s52, v107
	v_lshlrev_b32_e32 v114, 4, v81
	v_add_lshl_u32 v115, v112, v113, 9
	v_or_b32_e32 v88, v115, v114
	v_ashrrev_i32_e32 v89, 31, v88
	v_pk_mul_f32 v[82:83], s[30:31], v[2:3] op_sel_hi:[0,1]
	v_pk_mul_f32 v[80:81], s[30:31], v[0:1] op_sel_hi:[0,1]
	v_pk_mul_f32 v[96:97], s[30:31], v[6:7] op_sel_hi:[0,1]
	v_pk_mul_f32 v[98:99], s[30:31], v[4:5] op_sel_hi:[0,1]
	v_lshl_add_u64 v[90:91], s[34:35], 0, v[88:89]
	v_cvt_pk_bf16_f32 v80, v80, v81
	v_cvt_pk_bf16_f32 v81, v82, v83
	v_cvt_pk_bf16_f32 v82, v98, v99
	v_cvt_pk_bf16_f32 v83, v96, v97
	global_store_dwordx4 v[90:91], v[80:83], off sc1
	v_pk_mul_f32 v[98:99], s[30:31], v[62:63] op_sel_hi:[0,1]
	s_nop 0
	v_add_u32_e32 v80, 0x80, v104
	v_ashrrev_i32_e32 v80, 3, v80
	v_and_b32_e32 v153, -2, v80
	v_add_lshl_u32 v154, v153, v113, 9
	v_or_b32_e32 v90, v154, v114
	v_ashrrev_i32_e32 v91, 31, v90
	v_pk_mul_f32 v[82:83], s[30:31], v[54:55] op_sel_hi:[0,1]
	v_pk_mul_f32 v[80:81], s[30:31], v[52:53] op_sel_hi:[0,1]
	v_pk_mul_f32 v[104:105], s[30:31], v[60:61] op_sel_hi:[0,1]
	v_lshl_add_u64 v[96:97], s[34:35], 0, v[90:91]
	v_cvt_pk_bf16_f32 v80, v80, v81
	v_cvt_pk_bf16_f32 v81, v82, v83
	v_cvt_pk_bf16_f32 v82, v104, v105
	v_cvt_pk_bf16_f32 v83, v98, v99
	global_store_dwordx4 v[96:97], v[80:83], off sc1
	v_ashrrev_i32_e32 v89, 31, v115
	s_nop 0
	v_pk_mul_f32 v[82:83], s[30:31], v[10:11] op_sel_hi:[0,1]
	v_pk_mul_f32 v[80:81], s[30:31], v[8:9] op_sel_hi:[0,1]
	v_pk_mul_f32 v[96:97], s[30:31], v[18:19] op_sel_hi:[0,1]
	v_pk_mul_f32 v[98:99], s[30:31], v[16:17] op_sel_hi:[0,1]
	v_lshl_add_u64 v[88:89], s[34:35], 0, v[88:89]
	v_cvt_pk_bf16_f32 v80, v80, v81
	v_cvt_pk_bf16_f32 v81, v82, v83
	v_cvt_pk_bf16_f32 v82, v98, v99
	v_cvt_pk_bf16_f32 v83, v96, v97
	v_ashrrev_i32_e32 v91, 31, v154
	global_store_dwordx4 v[88:89], v[80:83], off offset:256 sc1
	v_lshl_add_u64 v[88:89], s[34:35], 0, v[90:91]
	v_pk_mul_f32 v[90:91], s[30:31], v[46:47] op_sel_hi:[0,1]
	v_pk_mul_f32 v[82:83], s[30:31], v[70:71] op_sel_hi:[0,1]
	v_pk_mul_f32 v[80:81], s[30:31], v[68:69] op_sel_hi:[0,1]
	v_pk_mul_f32 v[96:97], s[30:31], v[44:45] op_sel_hi:[0,1]
	v_cvt_pk_bf16_f32 v80, v80, v81
	v_cvt_pk_bf16_f32 v81, v82, v83
	v_cvt_pk_bf16_f32 v82, v96, v97
	v_cvt_pk_bf16_f32 v83, v90, v91
	global_store_dwordx4 v[88:89], v[80:83], off offset:256 sc1
	v_or_b32_e32 v104, 32, v113
	v_add_lshl_u32 v113, v104, v112, 9
	v_or_b32_e32 v88, v113, v114
	v_ashrrev_i32_e32 v89, 31, v88
	v_pk_mul_f32 v[82:83], s[30:31], v[26:27] op_sel_hi:[0,1]
	v_pk_mul_f32 v[80:81], s[30:31], v[24:25] op_sel_hi:[0,1]
	v_pk_mul_f32 v[96:97], s[30:31], v[34:35] op_sel_hi:[0,1]
	v_pk_mul_f32 v[98:99], s[30:31], v[32:33] op_sel_hi:[0,1]
	v_lshl_add_u64 v[90:91], s[34:35], 0, v[88:89]
	v_cvt_pk_bf16_f32 v80, v80, v81
	v_cvt_pk_bf16_f32 v81, v82, v83
	v_cvt_pk_bf16_f32 v82, v98, v99
	v_cvt_pk_bf16_f32 v83, v96, v97
	v_add_lshl_u32 v115, v153, v104, 9
	global_store_dwordx4 v[90:91], v[80:83], off sc1
	v_or_b32_e32 v90, v115, v114
	v_ashrrev_i32_e32 v91, 31, v90
	v_pk_mul_f32 v[82:83], s[30:31], v[38:39] op_sel_hi:[0,1]
	v_pk_mul_f32 v[80:81], s[30:31], v[36:37] op_sel_hi:[0,1]
	v_pk_mul_f32 v[98:99], s[30:31], v[30:31] op_sel_hi:[0,1]
	v_pk_mul_f32 v[104:105], s[30:31], v[28:29] op_sel_hi:[0,1]
	v_lshl_add_u64 v[96:97], s[34:35], 0, v[90:91]
	v_cvt_pk_bf16_f32 v80, v80, v81
	v_cvt_pk_bf16_f32 v81, v82, v83
	v_cvt_pk_bf16_f32 v82, v104, v105
	v_cvt_pk_bf16_f32 v83, v98, v99
	global_store_dwordx4 v[96:97], v[80:83], off sc1
	v_ashrrev_i32_e32 v89, 31, v113
	s_nop 0
	v_pk_mul_f32 v[82:83], s[30:31], v[42:43] op_sel_hi:[0,1]
	v_pk_mul_f32 v[80:81], s[30:31], v[40:41] op_sel_hi:[0,1]
	v_pk_mul_f32 v[96:97], s[30:31], v[50:51] op_sel_hi:[0,1]
	v_pk_mul_f32 v[98:99], s[30:31], v[48:49] op_sel_hi:[0,1]
	v_lshl_add_u64 v[88:89], s[34:35], 0, v[88:89]
	v_cvt_pk_bf16_f32 v80, v80, v81
	v_cvt_pk_bf16_f32 v81, v82, v83
	v_cvt_pk_bf16_f32 v82, v98, v99
	v_cvt_pk_bf16_f32 v83, v96, v97
	v_ashrrev_i32_e32 v91, 31, v115
	global_store_dwordx4 v[88:89], v[80:83], off offset:256 sc1
	v_lshl_add_u64 v[88:89], s[34:35], 0, v[90:91]
	v_pk_mul_f32 v[90:91], s[30:31], v[14:15] op_sel_hi:[0,1]
	v_pk_mul_f32 v[82:83], s[30:31], v[22:23] op_sel_hi:[0,1]
	v_pk_mul_f32 v[80:81], s[30:31], v[20:21] op_sel_hi:[0,1]
	v_pk_mul_f32 v[96:97], s[30:31], v[12:13] op_sel_hi:[0,1]
	v_cvt_pk_bf16_f32 v80, v80, v81
	v_cvt_pk_bf16_f32 v81, v82, v83
	v_cvt_pk_bf16_f32 v82, v96, v97
	v_cvt_pk_bf16_f32 v83, v90, v91
	global_store_dwordx4 v[88:89], v[80:83], off offset:256 sc1
	v_or_b32_e32 v98, s71, v107
	s_nop 0
	v_add_u32_e32 v80, v112, v98
	v_lshl_or_b32 v80, v80, 9, v114
	v_ashrrev_i32_e32 v81, 31, v80
	v_lshl_add_u64 v[88:89], s[34:35], 0, v[80:81]
	v_pk_mul_f32 v[82:83], s[30:31], v[146:147] op_sel_hi:[0,1]
	v_pk_mul_f32 v[80:81], s[30:31], v[144:145] op_sel_hi:[0,1]
	v_pk_mul_f32 v[90:91], s[30:31], v[142:143] op_sel_hi:[0,1]
	v_pk_mul_f32 v[96:97], s[30:31], v[140:141] op_sel_hi:[0,1]
	v_cvt_pk_bf16_f32 v80, v80, v81
	v_cvt_pk_bf16_f32 v81, v82, v83
	v_cvt_pk_bf16_f32 v82, v96, v97
	v_cvt_pk_bf16_f32 v83, v90, v91
	global_store_dwordx4 v[88:89], v[80:83], off sc1
	v_pk_mul_f32 v[90:91], s[30:31], v[86:87] op_sel_hi:[0,1]
	v_pk_mul_f32 v[96:97], s[30:31], v[84:85] op_sel_hi:[0,1]
	v_add_u32_e32 v80, v153, v98
	v_lshl_or_b32 v80, v80, 9, v114
	v_ashrrev_i32_e32 v81, 31, v80
	v_lshl_add_u64 v[88:89], s[34:35], 0, v[80:81]
	v_pk_mul_f32 v[82:83], s[30:31], v[78:79] op_sel_hi:[0,1]
	v_pk_mul_f32 v[80:81], s[30:31], v[76:77] op_sel_hi:[0,1]
	v_cvt_pk_bf16_f32 v80, v80, v81
	v_cvt_pk_bf16_f32 v81, v82, v83
	v_cvt_pk_bf16_f32 v82, v96, v97
	v_cvt_pk_bf16_f32 v83, v90, v91
	global_store_dwordx4 v[88:89], v[80:83], off sc1
	s_nop 1
	v_add_u32_e32 v80, 0x90, v106
	s_mov_b32 s2, 0x7fffffc0
	v_and_or_b32 v98, v80, s2, v107
	v_lshlrev_b32_e32 v80, 4, v80
	v_and_b32_e32 v99, 0x1f0, v80
	v_add_u32_e32 v80, v98, v112
	v_lshl_or_b32 v80, v80, 9, v99
	v_ashrrev_i32_e32 v81, 31, v80
	v_lshl_add_u64 v[88:89], s[34:35], 0, v[80:81]
	v_pk_mul_f32 v[82:83], s[30:31], v[138:139] op_sel_hi:[0,1]
	v_pk_mul_f32 v[80:81], s[30:31], v[136:137] op_sel_hi:[0,1]
	v_pk_mul_f32 v[90:91], s[30:31], v[134:135] op_sel_hi:[0,1]
	v_pk_mul_f32 v[96:97], s[30:31], v[132:133] op_sel_hi:[0,1]
	v_cvt_pk_bf16_f32 v80, v80, v81
	v_cvt_pk_bf16_f32 v81, v82, v83
	v_cvt_pk_bf16_f32 v82, v96, v97
	v_cvt_pk_bf16_f32 v83, v90, v91
	global_store_dwordx4 v[88:89], v[80:83], off sc1
	v_pk_mul_f32 v[90:91], s[30:31], v[102:103] op_sel_hi:[0,1]
	v_pk_mul_f32 v[96:97], s[30:31], v[100:101] op_sel_hi:[0,1]
	v_add_u32_e32 v80, v153, v98
	v_lshl_or_b32 v80, v80, 9, v99
	v_ashrrev_i32_e32 v81, 31, v80
	v_lshl_add_u64 v[88:89], s[34:35], 0, v[80:81]
	v_pk_mul_f32 v[82:83], s[30:31], v[94:95] op_sel_hi:[0,1]
	v_pk_mul_f32 v[80:81], s[30:31], v[92:93] op_sel_hi:[0,1]
	v_cvt_pk_bf16_f32 v80, v80, v81
	v_cvt_pk_bf16_f32 v81, v82, v83
	v_cvt_pk_bf16_f32 v82, v96, v97
	v_cvt_pk_bf16_f32 v83, v90, v91
	global_store_dwordx4 v[88:89], v[80:83], off sc1
	v_or_b32_e32 v98, s72, v107
	s_nop 0
	v_add_u32_e32 v80, v112, v98
	v_lshl_or_b32 v80, v80, 9, v114
	v_ashrrev_i32_e32 v81, 31, v80
	v_lshl_add_u64 v[88:89], s[34:35], 0, v[80:81]
	v_pk_mul_f32 v[82:83], s[30:31], v[130:131] op_sel_hi:[0,1]
	v_pk_mul_f32 v[80:81], s[30:31], v[128:129] op_sel_hi:[0,1]
	v_pk_mul_f32 v[90:91], s[30:31], v[58:59] op_sel_hi:[0,1]
	v_pk_mul_f32 v[96:97], s[30:31], v[56:57] op_sel_hi:[0,1]
	v_cvt_pk_bf16_f32 v80, v80, v81
	v_cvt_pk_bf16_f32 v81, v82, v83
	v_cvt_pk_bf16_f32 v82, v96, v97
	v_cvt_pk_bf16_f32 v83, v90, v91
	global_store_dwordx4 v[88:89], v[80:83], off sc1
	v_pk_mul_f32 v[90:91], s[30:31], v[118:119] op_sel_hi:[0,1]
	v_pk_mul_f32 v[96:97], s[30:31], v[116:117] op_sel_hi:[0,1]
	v_add_u32_e32 v80, v153, v98
	v_lshl_or_b32 v80, v80, 9, v114
	v_ashrrev_i32_e32 v81, 31, v80
	v_lshl_add_u64 v[88:89], s[34:35], 0, v[80:81]
	v_pk_mul_f32 v[82:83], s[30:31], v[110:111] op_sel_hi:[0,1]
	v_pk_mul_f32 v[80:81], s[30:31], v[108:109] op_sel_hi:[0,1]
	v_cvt_pk_bf16_f32 v80, v80, v81
	v_cvt_pk_bf16_f32 v81, v82, v83
	v_cvt_pk_bf16_f32 v82, v96, v97
	v_cvt_pk_bf16_f32 v83, v90, v91
	global_store_dwordx4 v[88:89], v[80:83], off sc1
	s_nop 1
	v_add_u32_e32 v80, 0xb0, v106
	s_mov_b32 s2, 0x7fffffe0
	v_and_or_b32 v98, v80, s2, v107
	v_lshlrev_b32_e32 v80, 4, v80
	v_and_b32_e32 v99, 0x1f0, v80
	v_add_u32_e32 v80, v98, v112
	v_lshl_or_b32 v80, v80, 9, v99
	v_ashrrev_i32_e32 v81, 31, v80
	v_lshl_add_u64 v[88:89], s[34:35], 0, v[80:81]
	v_pk_mul_f32 v[82:83], s[30:31], v[66:67] op_sel_hi:[0,1]
	v_pk_mul_f32 v[80:81], s[30:31], v[64:65] op_sel_hi:[0,1]
	v_pk_mul_f32 v[90:91], s[30:31], v[74:75] op_sel_hi:[0,1]
	v_pk_mul_f32 v[96:97], s[30:31], v[72:73] op_sel_hi:[0,1]
	v_cvt_pk_bf16_f32 v80, v80, v81
	v_cvt_pk_bf16_f32 v81, v82, v83
	v_cvt_pk_bf16_f32 v82, v96, v97
	v_cvt_pk_bf16_f32 v83, v90, v91
	global_store_dwordx4 v[88:89], v[80:83], off sc1
	v_pk_mul_f32 v[90:91], s[30:31], v[122:123] op_sel_hi:[0,1]
	v_pk_mul_f32 v[96:97], s[30:31], v[120:121] op_sel_hi:[0,1]
	v_add_u32_e32 v80, v153, v98
	v_lshl_or_b32 v80, v80, 9, v99
	v_ashrrev_i32_e32 v81, 31, v80
	v_lshl_add_u64 v[88:89], s[34:35], 0, v[80:81]
	v_pk_mul_f32 v[82:83], s[30:31], v[126:127] op_sel_hi:[0,1]
	v_pk_mul_f32 v[80:81], s[30:31], v[124:125] op_sel_hi:[0,1]
	v_cvt_pk_bf16_f32 v80, v80, v81
	v_cvt_pk_bf16_f32 v81, v82, v83
	v_cvt_pk_bf16_f32 v82, v96, v97
	v_cvt_pk_bf16_f32 v83, v90, v91
	global_store_dwordx4 v[88:89], v[80:83], off sc1
	v_pk_mul_f32 v[2:3], s[36:37], v[2:3] op_sel_hi:[0,1]
	v_pk_mul_f32 v[0:1], s[36:37], v[0:1] op_sel_hi:[0,1]
	v_pk_mul_f32 v[6:7], s[36:37], v[6:7] op_sel_hi:[0,1]
	v_pk_mul_f32 v[4:5], s[36:37], v[4:5] op_sel_hi:[0,1]
	v_pk_mul_f32 v[10:11], s[36:37], v[10:11] op_sel_hi:[0,1]
	v_pk_mul_f32 v[8:9], s[36:37], v[8:9] op_sel_hi:[0,1]
	v_pk_mul_f32 v[18:19], s[36:37], v[18:19] op_sel_hi:[0,1]
	v_pk_mul_f32 v[16:17], s[36:37], v[16:17] op_sel_hi:[0,1]
	v_pk_mul_f32 v[26:27], s[36:37], v[26:27] op_sel_hi:[0,1]
	v_pk_mul_f32 v[24:25], s[36:37], v[24:25] op_sel_hi:[0,1]
	v_pk_mul_f32 v[34:35], s[36:37], v[34:35] op_sel_hi:[0,1]
	v_pk_mul_f32 v[32:33], s[36:37], v[32:33] op_sel_hi:[0,1]
	v_pk_mul_f32 v[42:43], s[36:37], v[42:43] op_sel_hi:[0,1]
	v_pk_mul_f32 v[40:41], s[36:37], v[40:41] op_sel_hi:[0,1]
	v_pk_mul_f32 v[50:51], s[36:37], v[50:51] op_sel_hi:[0,1]
	v_pk_mul_f32 v[48:49], s[36:37], v[48:49] op_sel_hi:[0,1]
	v_pk_mul_f32 v[54:55], s[36:37], v[54:55] op_sel_hi:[0,1]
	v_pk_mul_f32 v[52:53], s[36:37], v[52:53] op_sel_hi:[0,1]
	v_pk_mul_f32 v[62:63], s[36:37], v[62:63] op_sel_hi:[0,1]
	v_pk_mul_f32 v[60:61], s[36:37], v[60:61] op_sel_hi:[0,1]
	v_pk_mul_f32 v[70:71], s[36:37], v[70:71] op_sel_hi:[0,1]
	v_pk_mul_f32 v[68:69], s[36:37], v[68:69] op_sel_hi:[0,1]
	v_pk_mul_f32 v[82:83], s[36:37], v[46:47] op_sel_hi:[0,1]
	v_pk_mul_f32 v[80:81], s[36:37], v[44:45] op_sel_hi:[0,1]
	v_pk_mul_f32 v[90:91], s[36:37], v[38:39] op_sel_hi:[0,1]
	v_pk_mul_f32 v[88:89], s[36:37], v[36:37] op_sel_hi:[0,1]
	v_pk_mul_f32 v[98:99], s[36:37], v[30:31] op_sel_hi:[0,1]
	v_pk_mul_f32 v[96:97], s[36:37], v[28:29] op_sel_hi:[0,1]
	v_pk_mul_f32 v[106:107], s[36:37], v[22:23] op_sel_hi:[0,1]
	v_pk_mul_f32 v[104:105], s[36:37], v[20:21] op_sel_hi:[0,1]
	v_pk_mul_f32 v[114:115], s[36:37], v[14:15] op_sel_hi:[0,1]
	v_pk_mul_f32 v[112:113], s[36:37], v[12:13] op_sel_hi:[0,1]
	v_pk_mul_f32 v[14:15], s[36:37], v[146:147] op_sel_hi:[0,1]
	v_pk_mul_f32 v[12:13], s[36:37], v[144:145] op_sel_hi:[0,1]
	v_pk_mul_f32 v[22:23], s[36:37], v[142:143] op_sel_hi:[0,1]
	v_pk_mul_f32 v[20:21], s[36:37], v[140:141] op_sel_hi:[0,1]
	v_pk_mul_f32 v[30:31], s[36:37], v[138:139] op_sel_hi:[0,1]
	v_pk_mul_f32 v[28:29], s[36:37], v[136:137] op_sel_hi:[0,1]
	v_pk_mul_f32 v[38:39], s[36:37], v[134:135] op_sel_hi:[0,1]
	v_pk_mul_f32 v[36:37], s[36:37], v[132:133] op_sel_hi:[0,1]
	v_pk_mul_f32 v[46:47], s[36:37], v[130:131] op_sel_hi:[0,1]
	v_pk_mul_f32 v[44:45], s[36:37], v[128:129] op_sel_hi:[0,1]
	v_pk_mul_f32 v[58:59], s[36:37], v[58:59] op_sel_hi:[0,1]
	v_pk_mul_f32 v[56:57], s[36:37], v[56:57] op_sel_hi:[0,1]
	v_pk_mul_f32 v[66:67], s[36:37], v[66:67] op_sel_hi:[0,1]
	v_pk_mul_f32 v[64:65], s[36:37], v[64:65] op_sel_hi:[0,1]
	v_pk_mul_f32 v[74:75], s[36:37], v[74:75] op_sel_hi:[0,1]
	v_pk_mul_f32 v[72:73], s[36:37], v[72:73] op_sel_hi:[0,1]
	v_pk_mul_f32 v[78:79], s[36:37], v[78:79] op_sel_hi:[0,1]
	v_pk_mul_f32 v[76:77], s[36:37], v[76:77] op_sel_hi:[0,1]
	v_pk_mul_f32 v[86:87], s[36:37], v[86:87] op_sel_hi:[0,1]
	v_pk_mul_f32 v[84:85], s[36:37], v[84:85] op_sel_hi:[0,1]
	v_pk_mul_f32 v[94:95], s[36:37], v[94:95] op_sel_hi:[0,1]
	v_pk_mul_f32 v[92:93], s[36:37], v[92:93] op_sel_hi:[0,1]
	v_pk_mul_f32 v[102:103], s[36:37], v[102:103] op_sel_hi:[0,1]
	v_pk_mul_f32 v[100:101], s[36:37], v[100:101] op_sel_hi:[0,1]
	v_pk_mul_f32 v[110:111], s[36:37], v[110:111] op_sel_hi:[0,1]
	v_pk_mul_f32 v[108:109], s[36:37], v[108:109] op_sel_hi:[0,1]
	v_pk_mul_f32 v[118:119], s[36:37], v[118:119] op_sel_hi:[0,1]
	v_pk_mul_f32 v[116:117], s[36:37], v[116:117] op_sel_hi:[0,1]
	v_pk_mul_f32 v[126:127], s[36:37], v[126:127] op_sel_hi:[0,1]
	v_pk_mul_f32 v[124:125], s[36:37], v[124:125] op_sel_hi:[0,1]
	v_pk_mul_f32 v[122:123], s[36:37], v[122:123] op_sel_hi:[0,1]
	v_pk_mul_f32 v[120:121], s[36:37], v[120:121] op_sel_hi:[0,1]
	s_andn2_b64 vcc, exec, s[38:39]
	s_mov_b64 s[4:5], -1
	s_cbranch_vccnz .LBB0_445
	s_andn2_b64 vcc, exec, s[18:19]
	s_cbranch_vccnz .LBB0_444
	s_barrier
	s_branch .LBB0_444

.LBB0_474:
	v_mbcnt_lo_u32_b32 v4, -1, 0
	v_mbcnt_hi_u32_b32 v4, -1, v4
	s_nop 0
	v_and_or_b32 v12, v4, 15, s52
	v_ashrrev_i32_e32 v4, 1, v4
	v_and_b32_e32 v4, -8, v4
	v_add_u32_e32 v4, s53, v4
	v_ashrrev_i32_e32 v5, 31, v4
	v_lshlrev_b64 v[4:5], 1, v[4:5]
	v_mul_f32_e32 v69, s50, v242
	v_mul_f32_e32 v70, s50, v243
	v_mul_f32_e32 v71, s50, v120
	v_mul_f32_e32 v80, s50, v121
	v_mul_f32_e32 v69, 0xbfb8aa3b, v69
	v_mul_f32_e32 v70, 0xbfb8aa3b, v70
	v_mul_f32_e32 v71, 0xbfb8aa3b, v71
	v_mul_f32_e32 v80, 0xbfb8aa3b, v80
	v_exp_f32_e32 v69, v69
	v_exp_f32_e32 v70, v70
	v_exp_f32_e32 v71, v71
	v_exp_f32_e32 v80, v80
	v_mul_f32_e32 v13, s50, v240
	v_mul_f32_e32 v68, s50, v241
	v_mul_f32_e32 v81, s50, v122
	v_mul_f32_e32 v82, s50, v123
	v_mul_f32_e32 v13, 0xbfb8aa3b, v13
	v_mul_f32_e32 v68, 0xbfb8aa3b, v68
	v_add_f32_e32 v69, 1.0, v69
	v_add_f32_e32 v70, 1.0, v70
	v_add_f32_e32 v71, 1.0, v71
	v_add_f32_e32 v80, 1.0, v80
	v_mul_f32_e32 v81, 0xbfb8aa3b, v81
	v_mul_f32_e32 v82, 0xbfb8aa3b, v82
	v_exp_f32_e32 v13, v13
	v_exp_f32_e32 v68, v68
	v_rcp_f32_e32 v69, v69
	v_rcp_f32_e32 v70, v70
	v_rcp_f32_e32 v71, v71
	v_exp_f32_e32 v81, v81
	v_exp_f32_e32 v82, v82
	v_rcp_f32_e32 v80, v80
	v_add_f32_e32 v13, 1.0, v13
	v_add_f32_e32 v68, 1.0, v68
	v_add_f32_e32 v81, 1.0, v81
	v_add_f32_e32 v82, 1.0, v82
	v_cvt_pk_bf16_f32 v69, v69, v70
	v_cvt_pk_bf16_f32 v70, v71, v80
	v_mul_f32_e32 v80, s50, v185
	v_rcp_f32_e32 v13, v13
	v_rcp_f32_e32 v68, v68
	v_rcp_f32_e32 v81, v81
	v_rcp_f32_e32 v82, v82
	v_mul_f32_e32 v80, 0xbfb8aa3b, v80
	v_exp_f32_e32 v80, v80
	v_mov_b64_e32 v[6:7], s[34:35]
	v_mad_u64_u32 v[14:15], s[2:3], v12, s25, v[6:7]
	v_lshl_add_u64 v[14:15], v[14:15], 0, v[4:5]
	v_cvt_pk_bf16_f32 v68, v13, v68
	v_cvt_pk_bf16_f32 v71, v81, v82
	v_mul_f32_e32 v13, s50, v184
	global_store_dwordx4 v[14:15], v[68:71], off sc1
	v_mul_f32_e32 v81, s50, v182
	v_mul_f32_e32 v82, s50, v183
	v_add_f32_e32 v68, 1.0, v80
	v_mul_f32_e32 v69, s50, v186
	v_mul_f32_e32 v70, s50, v187
	v_mul_f32_e32 v71, s50, v180
	v_mul_f32_e32 v80, s50, v181
	v_mul_f32_e32 v13, 0xbfb8aa3b, v13
	v_mul_f32_e32 v69, 0xbfb8aa3b, v69
	v_mul_f32_e32 v70, 0xbfb8aa3b, v70
	v_mul_f32_e32 v71, 0xbfb8aa3b, v71
	v_mul_f32_e32 v80, 0xbfb8aa3b, v80
	v_mul_f32_e32 v81, 0xbfb8aa3b, v81
	v_mul_f32_e32 v82, 0xbfb8aa3b, v82
	v_exp_f32_e32 v13, v13
	v_exp_f32_e32 v69, v69
	v_exp_f32_e32 v70, v70
	v_exp_f32_e32 v71, v71
	v_exp_f32_e32 v80, v80
	v_exp_f32_e32 v81, v81
	v_exp_f32_e32 v82, v82
	v_add_f32_e32 v13, 1.0, v13
	v_add_f32_e32 v69, 1.0, v69
	v_add_f32_e32 v70, 1.0, v70
	v_add_f32_e32 v71, 1.0, v71
	v_add_f32_e32 v80, 1.0, v80
	v_add_f32_e32 v81, 1.0, v81
	v_add_f32_e32 v82, 1.0, v82
	v_rcp_f32_e32 v13, v13
	v_rcp_f32_e32 v68, v68
	v_rcp_f32_e32 v69, v69
	v_rcp_f32_e32 v70, v70
	v_rcp_f32_e32 v71, v71
	v_rcp_f32_e32 v80, v80
	v_rcp_f32_e32 v81, v81
	v_rcp_f32_e32 v82, v82
	v_cvt_pk_bf16_f32 v68, v13, v68
	v_cvt_pk_bf16_f32 v69, v69, v70
	v_cvt_pk_bf16_f32 v70, v71, v80
	v_cvt_pk_bf16_f32 v71, v81, v82
	global_store_dwordx4 v[14:15], v[68:71], off offset:256 sc1
	s_nop 1
	v_mul_f32_e32 v69, s50, v114
	v_mul_f32_e32 v70, s50, v115
	v_mul_f32_e32 v71, s50, v104
	v_mul_f32_e32 v80, s50, v105
	v_mul_f32_e32 v69, 0xbfb8aa3b, v69
	v_mul_f32_e32 v70, 0xbfb8aa3b, v70
	v_mul_f32_e32 v71, 0xbfb8aa3b, v71
	v_mul_f32_e32 v80, 0xbfb8aa3b, v80
	v_exp_f32_e32 v69, v69
	v_exp_f32_e32 v70, v70
	v_exp_f32_e32 v71, v71
	v_exp_f32_e32 v80, v80
	v_or_b32_e32 v13, 16, v12
	v_mad_u64_u32 v[14:15], s[2:3], v13, s25, v[6:7]
	v_mul_f32_e32 v13, s50, v112
	v_mul_f32_e32 v68, s50, v113
	v_mul_f32_e32 v81, s50, v106
	v_mul_f32_e32 v82, s50, v107
	v_mul_f32_e32 v13, 0xbfb8aa3b, v13
	v_mul_f32_e32 v68, 0xbfb8aa3b, v68
	v_add_f32_e32 v69, 1.0, v69
	v_add_f32_e32 v70, 1.0, v70
	v_add_f32_e32 v71, 1.0, v71
	v_add_f32_e32 v80, 1.0, v80
	v_mul_f32_e32 v81, 0xbfb8aa3b, v81
	v_mul_f32_e32 v82, 0xbfb8aa3b, v82
	v_exp_f32_e32 v13, v13
	v_exp_f32_e32 v68, v68
	v_rcp_f32_e32 v69, v69
	v_rcp_f32_e32 v70, v70
	v_rcp_f32_e32 v71, v71
	v_exp_f32_e32 v81, v81
	v_exp_f32_e32 v82, v82
	v_rcp_f32_e32 v80, v80
	v_add_f32_e32 v13, 1.0, v13
	v_add_f32_e32 v68, 1.0, v68
	v_add_f32_e32 v81, 1.0, v81
	v_add_f32_e32 v82, 1.0, v82
	v_cvt_pk_bf16_f32 v69, v69, v70
	v_cvt_pk_bf16_f32 v70, v71, v80
	v_mul_f32_e32 v80, s50, v117
	v_rcp_f32_e32 v13, v13
	v_rcp_f32_e32 v68, v68
	v_rcp_f32_e32 v81, v81
	v_rcp_f32_e32 v82, v82
	v_mul_f32_e32 v80, 0xbfb8aa3b, v80
	v_exp_f32_e32 v80, v80
	v_lshl_add_u64 v[14:15], v[14:15], 0, v[4:5]
	v_cvt_pk_bf16_f32 v68, v13, v68
	v_cvt_pk_bf16_f32 v71, v81, v82
	v_mul_f32_e32 v13, s50, v116
	global_store_dwordx4 v[14:15], v[68:71], off sc1
	v_mul_f32_e32 v81, s50, v110
	v_mul_f32_e32 v82, s50, v111
	v_add_f32_e32 v68, 1.0, v80
	v_mul_f32_e32 v69, s50, v118
	v_mul_f32_e32 v70, s50, v119
	v_mul_f32_e32 v71, s50, v108
	v_mul_f32_e32 v80, s50, v109
	v_mul_f32_e32 v13, 0xbfb8aa3b, v13
	v_mul_f32_e32 v69, 0xbfb8aa3b, v69
	v_mul_f32_e32 v70, 0xbfb8aa3b, v70
	v_mul_f32_e32 v71, 0xbfb8aa3b, v71
	v_mul_f32_e32 v80, 0xbfb8aa3b, v80
	v_mul_f32_e32 v81, 0xbfb8aa3b, v81
	v_mul_f32_e32 v82, 0xbfb8aa3b, v82
	v_exp_f32_e32 v13, v13
	v_exp_f32_e32 v69, v69
	v_exp_f32_e32 v70, v70
	v_exp_f32_e32 v71, v71
	v_exp_f32_e32 v80, v80
	v_exp_f32_e32 v81, v81
	v_exp_f32_e32 v82, v82
	v_add_f32_e32 v13, 1.0, v13
	v_add_f32_e32 v69, 1.0, v69
	v_add_f32_e32 v70, 1.0, v70
	v_add_f32_e32 v71, 1.0, v71
	v_add_f32_e32 v80, 1.0, v80
	v_add_f32_e32 v81, 1.0, v81
	v_add_f32_e32 v82, 1.0, v82
	v_rcp_f32_e32 v13, v13
	v_rcp_f32_e32 v68, v68
	v_rcp_f32_e32 v69, v69
	v_rcp_f32_e32 v70, v70
	v_rcp_f32_e32 v71, v71
	v_rcp_f32_e32 v80, v80
	v_rcp_f32_e32 v81, v81
	v_rcp_f32_e32 v82, v82
	v_cvt_pk_bf16_f32 v68, v13, v68
	v_cvt_pk_bf16_f32 v69, v69, v70
	v_cvt_pk_bf16_f32 v70, v71, v80
	v_cvt_pk_bf16_f32 v71, v81, v82
	global_store_dwordx4 v[14:15], v[68:71], off offset:256 sc1
	s_nop 1
	v_mul_f32_e32 v69, s50, v102
	v_mul_f32_e32 v70, s50, v103
	v_mul_f32_e32 v71, s50, v92
	v_mul_f32_e32 v80, s50, v93
	v_mul_f32_e32 v69, 0xbfb8aa3b, v69
	v_mul_f32_e32 v70, 0xbfb8aa3b, v70
	v_mul_f32_e32 v71, 0xbfb8aa3b, v71
	v_mul_f32_e32 v80, 0xbfb8aa3b, v80
	v_exp_f32_e32 v69, v69
	v_exp_f32_e32 v70, v70
	v_exp_f32_e32 v71, v71
	v_exp_f32_e32 v80, v80
	v_or_b32_e32 v13, 32, v12
	v_mad_u64_u32 v[14:15], s[2:3], v13, s25, v[6:7]
	v_mul_f32_e32 v13, s50, v100
	v_mul_f32_e32 v68, s50, v101
	v_mul_f32_e32 v81, s50, v94
	v_mul_f32_e32 v82, s50, v95
	v_mul_f32_e32 v13, 0xbfb8aa3b, v13
	v_mul_f32_e32 v68, 0xbfb8aa3b, v68
	v_add_f32_e32 v69, 1.0, v69
	v_add_f32_e32 v70, 1.0, v70
	v_add_f32_e32 v71, 1.0, v71
	v_add_f32_e32 v80, 1.0, v80
	v_mul_f32_e32 v81, 0xbfb8aa3b, v81
	v_mul_f32_e32 v82, 0xbfb8aa3b, v82
	v_exp_f32_e32 v13, v13
	v_exp_f32_e32 v68, v68
	v_rcp_f32_e32 v69, v69
	v_rcp_f32_e32 v70, v70
	v_rcp_f32_e32 v71, v71
	v_exp_f32_e32 v81, v81
	v_exp_f32_e32 v82, v82
	v_rcp_f32_e32 v80, v80
	v_add_f32_e32 v13, 1.0, v13
	v_add_f32_e32 v68, 1.0, v68
	v_add_f32_e32 v81, 1.0, v81
	v_add_f32_e32 v82, 1.0, v82
	v_cvt_pk_bf16_f32 v69, v69, v70
	v_cvt_pk_bf16_f32 v70, v71, v80
	v_mul_f32_e32 v80, s50, v97
	v_rcp_f32_e32 v13, v13
	v_rcp_f32_e32 v68, v68
	v_rcp_f32_e32 v81, v81
	v_rcp_f32_e32 v82, v82
	v_mul_f32_e32 v80, 0xbfb8aa3b, v80
	v_exp_f32_e32 v80, v80
	v_lshl_add_u64 v[14:15], v[14:15], 0, v[4:5]
	v_cvt_pk_bf16_f32 v68, v13, v68
	v_cvt_pk_bf16_f32 v71, v81, v82
	v_mul_f32_e32 v13, s50, v96
	global_store_dwordx4 v[14:15], v[68:71], off sc1
	v_mul_f32_e32 v81, s50, v90
	v_mul_f32_e32 v82, s50, v91
	v_add_f32_e32 v68, 1.0, v80
	v_mul_f32_e32 v69, s50, v98
	v_mul_f32_e32 v70, s50, v99
	v_mul_f32_e32 v71, s50, v88
	v_mul_f32_e32 v80, s50, v89
	v_mul_f32_e32 v13, 0xbfb8aa3b, v13
	v_mul_f32_e32 v69, 0xbfb8aa3b, v69
	v_mul_f32_e32 v70, 0xbfb8aa3b, v70
	v_mul_f32_e32 v71, 0xbfb8aa3b, v71
	v_mul_f32_e32 v80, 0xbfb8aa3b, v80
	v_mul_f32_e32 v81, 0xbfb8aa3b, v81
	v_mul_f32_e32 v82, 0xbfb8aa3b, v82
	v_exp_f32_e32 v13, v13
	v_exp_f32_e32 v69, v69
	v_exp_f32_e32 v70, v70
	v_exp_f32_e32 v71, v71
	v_exp_f32_e32 v80, v80
	v_exp_f32_e32 v81, v81
	v_exp_f32_e32 v82, v82
	v_add_f32_e32 v13, 1.0, v13
	v_add_f32_e32 v69, 1.0, v69
	v_add_f32_e32 v70, 1.0, v70
	v_add_f32_e32 v71, 1.0, v71
	v_add_f32_e32 v80, 1.0, v80
	v_add_f32_e32 v81, 1.0, v81
	v_add_f32_e32 v82, 1.0, v82
	v_rcp_f32_e32 v13, v13
	v_rcp_f32_e32 v68, v68
	v_rcp_f32_e32 v69, v69
	v_rcp_f32_e32 v70, v70
	v_rcp_f32_e32 v71, v71
	v_rcp_f32_e32 v80, v80
	v_rcp_f32_e32 v81, v81
	v_rcp_f32_e32 v82, v82
	v_cvt_pk_bf16_f32 v68, v13, v68
	v_cvt_pk_bf16_f32 v69, v69, v70
	v_cvt_pk_bf16_f32 v70, v71, v80
	v_cvt_pk_bf16_f32 v71, v81, v82
	global_store_dwordx4 v[14:15], v[68:71], off offset:256 sc1
	v_or_b32_e32 v13, 48, v12
	v_mad_u64_u32 v[14:15], s[2:3], v13, s25, v[6:7]
	v_mul_f32_e32 v13, s50, v188
	v_mul_f32_e32 v68, s50, v189
	v_mul_f32_e32 v69, s50, v190
	v_mul_f32_e32 v70, s50, v191
	v_mul_f32_e32 v71, s50, v144
	v_mul_f32_e32 v80, s50, v145
	v_mul_f32_e32 v81, s50, v146
	v_mul_f32_e32 v82, s50, v147
	v_mul_f32_e32 v13, 0xbfb8aa3b, v13
	v_mul_f32_e32 v68, 0xbfb8aa3b, v68
	v_mul_f32_e32 v69, 0xbfb8aa3b, v69
	v_mul_f32_e32 v70, 0xbfb8aa3b, v70
	v_mul_f32_e32 v71, 0xbfb8aa3b, v71
	v_mul_f32_e32 v80, 0xbfb8aa3b, v80
	v_mul_f32_e32 v81, 0xbfb8aa3b, v81
	v_mul_f32_e32 v82, 0xbfb8aa3b, v82
	v_exp_f32_e32 v13, v13
	v_exp_f32_e32 v68, v68
	v_exp_f32_e32 v69, v69
	v_exp_f32_e32 v70, v70
	v_exp_f32_e32 v71, v71
	v_exp_f32_e32 v80, v80
	v_exp_f32_e32 v81, v81
	v_exp_f32_e32 v82, v82
	v_mul_f32_e32 v56, s50, v56
	v_add_f32_e32 v13, 1.0, v13
	v_add_f32_e32 v68, 1.0, v68
	v_add_f32_e32 v69, 1.0, v69
	v_add_f32_e32 v70, 1.0, v70
	v_add_f32_e32 v71, 1.0, v71
	v_add_f32_e32 v80, 1.0, v80
	v_add_f32_e32 v81, 1.0, v81
	v_add_f32_e32 v82, 1.0, v82
	v_mul_f32_e32 v56, 0xbfb8aa3b, v56
	v_mul_f32_e32 v57, s50, v57
	v_rcp_f32_e32 v13, v13
	v_rcp_f32_e32 v68, v68
	v_rcp_f32_e32 v69, v69
	v_rcp_f32_e32 v70, v70
	v_rcp_f32_e32 v71, v71
	v_rcp_f32_e32 v80, v80
	v_rcp_f32_e32 v81, v81
	v_rcp_f32_e32 v82, v82
	v_exp_f32_e32 v56, v56
	v_mul_f32_e32 v57, 0xbfb8aa3b, v57
	v_exp_f32_e32 v57, v57
	v_lshl_add_u64 v[14:15], v[14:15], 0, v[4:5]
	v_cvt_pk_bf16_f32 v68, v13, v68
	v_cvt_pk_bf16_f32 v69, v69, v70
	v_cvt_pk_bf16_f32 v70, v71, v80
	v_cvt_pk_bf16_f32 v71, v81, v82
	v_add_f32_e32 v56, 1.0, v56
	global_store_dwordx4 v[14:15], v[68:71], off sc1
	v_mul_f32_e32 v13, s50, v72
	v_mul_f32_e32 v72, s50, v73
	v_rcp_f32_e32 v71, v56
	v_add_f32_e32 v56, 1.0, v57
	v_mul_f32_e32 v57, s50, v58
	v_mul_f32_e32 v69, s50, v74
	v_mul_f32_e32 v70, s50, v75
	v_mul_f32_e32 v57, 0xbfb8aa3b, v57
	v_mul_f32_e32 v58, s50, v59
	v_mul_f32_e32 v13, 0xbfb8aa3b, v13
	v_mul_f32_e32 v72, 0xbfb8aa3b, v72
	v_mul_f32_e32 v69, 0xbfb8aa3b, v69
	v_mul_f32_e32 v70, 0xbfb8aa3b, v70
	v_exp_f32_e32 v57, v57
	v_mul_f32_e32 v58, 0xbfb8aa3b, v58
	v_exp_f32_e32 v13, v13
	v_exp_f32_e32 v72, v72
	v_exp_f32_e32 v69, v69
	v_exp_f32_e32 v70, v70
	v_exp_f32_e32 v58, v58
	v_rcp_f32_e32 v59, v56
	v_add_f32_e32 v56, 1.0, v57
	v_add_f32_e32 v13, 1.0, v13
	v_add_f32_e32 v68, 1.0, v72
	v_add_f32_e32 v69, 1.0, v69
	v_add_f32_e32 v70, 1.0, v70
	v_rcp_f32_e32 v72, v56
	v_add_f32_e32 v56, 1.0, v58
	v_rcp_f32_e32 v13, v13
	v_rcp_f32_e32 v68, v68
	v_rcp_f32_e32 v69, v69
	v_rcp_f32_e32 v70, v70
	v_rcp_f32_e32 v73, v56
	v_cvt_pk_bf16_f32 v56, v13, v68
	v_cvt_pk_bf16_f32 v58, v71, v59
	v_cvt_pk_bf16_f32 v57, v69, v70
	v_cvt_pk_bf16_f32 v59, v72, v73
	global_store_dwordx4 v[14:15], v[56:59], off offset:256 sc1
	v_add_u32_e32 v13, 0x80, v12
	v_mad_u64_u32 v[14:15], s[2:3], v13, s25, v[6:7]
	v_mul_f32_e32 v13, s50, v84
	v_mul_f32_e32 v56, s50, v85
	v_mul_f32_e32 v57, s50, v86
	v_mul_f32_e32 v58, s50, v87
	v_mul_f32_e32 v59, s50, v64
	v_mul_f32_e32 v64, s50, v65
	v_mul_f32_e32 v65, s50, v66
	v_mul_f32_e32 v66, s50, v67
	v_mul_f32_e32 v13, 0xbfb8aa3b, v13
	v_mul_f32_e32 v56, 0xbfb8aa3b, v56
	v_mul_f32_e32 v57, 0xbfb8aa3b, v57
	v_mul_f32_e32 v58, 0xbfb8aa3b, v58
	v_mul_f32_e32 v59, 0xbfb8aa3b, v59
	v_mul_f32_e32 v64, 0xbfb8aa3b, v64
	v_mul_f32_e32 v65, 0xbfb8aa3b, v65
	v_mul_f32_e32 v66, 0xbfb8aa3b, v66
	v_exp_f32_e32 v13, v13
	v_exp_f32_e32 v56, v56
	v_exp_f32_e32 v57, v57
	v_exp_f32_e32 v58, v58
	v_exp_f32_e32 v59, v59
	v_exp_f32_e32 v64, v64
	v_exp_f32_e32 v65, v65
	v_exp_f32_e32 v66, v66
	v_add_f32_e32 v13, 1.0, v13
	v_add_f32_e32 v56, 1.0, v56
	v_add_f32_e32 v57, 1.0, v57
	v_add_f32_e32 v58, 1.0, v58
	v_add_f32_e32 v59, 1.0, v59
	v_add_f32_e32 v64, 1.0, v64
	v_add_f32_e32 v65, 1.0, v65
	v_add_f32_e32 v66, 1.0, v66
	v_rcp_f32_e32 v13, v13
	v_rcp_f32_e32 v56, v56
	v_rcp_f32_e32 v57, v57
	v_rcp_f32_e32 v58, v58
	v_rcp_f32_e32 v59, v59
	v_rcp_f32_e32 v64, v64
	v_rcp_f32_e32 v65, v65
	v_rcp_f32_e32 v66, v66
	v_lshl_add_u64 v[14:15], v[14:15], 0, v[4:5]
	v_cvt_pk_bf16_f32 v56, v13, v56
	v_cvt_pk_bf16_f32 v57, v57, v58
	v_cvt_pk_bf16_f32 v58, v59, v64
	v_cvt_pk_bf16_f32 v59, v65, v66
	v_mul_f32_e32 v13, s50, v76
	v_mul_f32_e32 v64, s50, v77
	global_store_dwordx4 v[14:15], v[56:59], off sc1
	v_mul_f32_e32 v13, 0xbfb8aa3b, v13
	v_mul_f32_e32 v64, 0xbfb8aa3b, v64
	v_mul_f32_e32 v57, s50, v78
	v_mul_f32_e32 v58, s50, v79
	v_mul_f32_e32 v59, s50, v60
	v_mul_f32_e32 v60, s50, v61
	v_mul_f32_e32 v61, s50, v62
	v_mul_f32_e32 v62, s50, v63
	v_mul_f32_e32 v57, 0xbfb8aa3b, v57
	v_mul_f32_e32 v58, 0xbfb8aa3b, v58
	v_mul_f32_e32 v59, 0xbfb8aa3b, v59
	v_mul_f32_e32 v60, 0xbfb8aa3b, v60
	v_mul_f32_e32 v61, 0xbfb8aa3b, v61
	v_mul_f32_e32 v62, 0xbfb8aa3b, v62
	v_exp_f32_e32 v13, v13
	v_exp_f32_e32 v64, v64
	v_exp_f32_e32 v57, v57
	v_exp_f32_e32 v58, v58
	v_exp_f32_e32 v59, v59
	v_exp_f32_e32 v60, v60
	v_exp_f32_e32 v61, v61
	v_exp_f32_e32 v62, v62
	v_add_f32_e32 v13, 1.0, v13
	v_add_f32_e32 v56, 1.0, v64
	v_add_f32_e32 v57, 1.0, v57
	v_add_f32_e32 v58, 1.0, v58
	v_add_f32_e32 v59, 1.0, v59
	v_add_f32_e32 v60, 1.0, v60
	v_add_f32_e32 v61, 1.0, v61
	v_add_f32_e32 v62, 1.0, v62
	v_rcp_f32_e32 v13, v13
	v_rcp_f32_e32 v56, v56
	v_rcp_f32_e32 v57, v57
	v_rcp_f32_e32 v58, v58
	v_rcp_f32_e32 v59, v59
	v_rcp_f32_e32 v60, v60
	v_rcp_f32_e32 v61, v61
	v_rcp_f32_e32 v62, v62
	v_cvt_pk_bf16_f32 v56, v13, v56
	v_cvt_pk_bf16_f32 v57, v57, v58
	v_cvt_pk_bf16_f32 v58, v59, v60
	v_cvt_pk_bf16_f32 v59, v61, v62
	global_store_dwordx4 v[14:15], v[56:59], off offset:256 sc1
	v_mul_f32_e32 v44, s50, v44
	v_mul_f32_e32 v44, 0xbfb8aa3b, v44
	v_mul_f32_e32 v45, s50, v45
	v_exp_f32_e32 v44, v44
	v_mul_f32_e32 v45, 0xbfb8aa3b, v45
	v_exp_f32_e32 v45, v45
	v_add_u32_e32 v13, 0x90, v12
	v_add_f32_e32 v44, 1.0, v44
	v_mad_u64_u32 v[14:15], s[2:3], v13, s25, v[6:7]
	v_mul_f32_e32 v13, s50, v52
	v_mul_f32_e32 v52, s50, v53
	v_mul_f32_e32 v53, s50, v54
	v_mul_f32_e32 v54, s50, v55
	v_rcp_f32_e32 v55, v44
	v_add_f32_e32 v44, 1.0, v45
	v_mul_f32_e32 v45, s50, v46
	v_mul_f32_e32 v45, 0xbfb8aa3b, v45
	v_mul_f32_e32 v46, s50, v47
	v_mul_f32_e32 v13, 0xbfb8aa3b, v13
	v_mul_f32_e32 v52, 0xbfb8aa3b, v52
	v_mul_f32_e32 v53, 0xbfb8aa3b, v53
	v_mul_f32_e32 v54, 0xbfb8aa3b, v54
	v_exp_f32_e32 v45, v45
	v_mul_f32_e32 v46, 0xbfb8aa3b, v46
	v_exp_f32_e32 v13, v13
	v_exp_f32_e32 v52, v52
	v_exp_f32_e32 v53, v53
	v_exp_f32_e32 v54, v54
	v_exp_f32_e32 v46, v46
	v_rcp_f32_e32 v47, v44
	v_add_f32_e32 v44, 1.0, v45
	v_mul_f32_e32 v40, s50, v40
	v_add_f32_e32 v13, 1.0, v13
	v_add_f32_e32 v52, 1.0, v52
	v_add_f32_e32 v53, 1.0, v53
	v_add_f32_e32 v54, 1.0, v54
	v_rcp_f32_e32 v56, v44
	v_add_f32_e32 v44, 1.0, v46
	v_mul_f32_e32 v40, 0xbfb8aa3b, v40
	v_mul_f32_e32 v41, s50, v41
	v_rcp_f32_e32 v13, v13
	v_rcp_f32_e32 v52, v52
	v_rcp_f32_e32 v53, v53
	v_rcp_f32_e32 v54, v54
	v_rcp_f32_e32 v57, v44
	v_exp_f32_e32 v40, v40
	v_mul_f32_e32 v41, 0xbfb8aa3b, v41
	v_exp_f32_e32 v41, v41
	v_lshl_add_u64 v[14:15], v[14:15], 0, v[4:5]
	v_cvt_pk_bf16_f32 v44, v13, v52
	v_cvt_pk_bf16_f32 v45, v53, v54
	v_cvt_pk_bf16_f32 v46, v55, v47
	v_cvt_pk_bf16_f32 v47, v56, v57
	v_add_f32_e32 v40, 1.0, v40
	global_store_dwordx4 v[14:15], v[44:47], off sc1
	v_mul_f32_e32 v13, s50, v48
	v_mul_f32_e32 v48, s50, v49
	v_rcp_f32_e32 v47, v40
	v_add_f32_e32 v40, 1.0, v41
	v_mul_f32_e32 v41, s50, v42
	v_mul_f32_e32 v45, s50, v50
	v_mul_f32_e32 v46, s50, v51
	v_mul_f32_e32 v41, 0xbfb8aa3b, v41
	v_mul_f32_e32 v42, s50, v43
	v_mul_f32_e32 v13, 0xbfb8aa3b, v13
	v_mul_f32_e32 v48, 0xbfb8aa3b, v48
	v_mul_f32_e32 v45, 0xbfb8aa3b, v45
	v_mul_f32_e32 v46, 0xbfb8aa3b, v46
	v_exp_f32_e32 v41, v41
	v_mul_f32_e32 v42, 0xbfb8aa3b, v42
	v_exp_f32_e32 v13, v13
	v_exp_f32_e32 v48, v48
	v_exp_f32_e32 v45, v45
	v_exp_f32_e32 v46, v46
	v_exp_f32_e32 v42, v42
	v_rcp_f32_e32 v43, v40
	v_add_f32_e32 v40, 1.0, v41
	v_add_f32_e32 v13, 1.0, v13
	v_add_f32_e32 v44, 1.0, v48
	v_add_f32_e32 v45, 1.0, v45
	v_add_f32_e32 v46, 1.0, v46
	v_rcp_f32_e32 v48, v40
	v_add_f32_e32 v40, 1.0, v42
	v_rcp_f32_e32 v13, v13
	v_rcp_f32_e32 v44, v44
	v_rcp_f32_e32 v45, v45
	v_rcp_f32_e32 v46, v46
	v_rcp_f32_e32 v49, v40
	v_cvt_pk_bf16_f32 v40, v13, v44
	v_cvt_pk_bf16_f32 v42, v47, v43
	v_cvt_pk_bf16_f32 v41, v45, v46
	v_cvt_pk_bf16_f32 v43, v48, v49
	global_store_dwordx4 v[14:15], v[40:43], off offset:256 sc1
	v_mul_f32_e32 v32, s50, v32
	v_mul_f32_e32 v32, 0xbfb8aa3b, v32
	v_mul_f32_e32 v33, s50, v33
	v_exp_f32_e32 v32, v32
	v_mul_f32_e32 v33, 0xbfb8aa3b, v33
	v_add_u32_e32 v13, 0xa0, v12
	v_exp_f32_e32 v33, v33
	v_mad_u64_u32 v[14:15], s[2:3], v13, s25, v[6:7]
	v_mul_f32_e32 v13, s50, v36
	v_mul_f32_e32 v36, s50, v37
	v_mul_f32_e32 v13, 0xbfb8aa3b, v13
	v_mul_f32_e32 v36, 0xbfb8aa3b, v36
	v_exp_f32_e32 v13, v13
	v_exp_f32_e32 v36, v36
	v_add_f32_e32 v32, 1.0, v32
	v_mul_f32_e32 v37, s50, v38
	v_mul_f32_e32 v38, s50, v39
	v_rcp_f32_e32 v39, v32
	v_add_f32_e32 v32, 1.0, v33
	v_mul_f32_e32 v33, s50, v34
	v_mul_f32_e32 v33, 0xbfb8aa3b, v33
	v_mul_f32_e32 v34, s50, v35
	v_mul_f32_e32 v20, s50, v20
	v_exp_f32_e32 v33, v33
	v_mul_f32_e32 v34, 0xbfb8aa3b, v34
	v_mul_f32_e32 v20, 0xbfb8aa3b, v20
	v_mul_f32_e32 v21, s50, v21
	v_add_f32_e32 v13, 1.0, v13
	v_add_f32_e32 v36, 1.0, v36
	v_exp_f32_e32 v34, v34
	v_exp_f32_e32 v20, v20
	v_mul_f32_e32 v21, 0xbfb8aa3b, v21
	v_rcp_f32_e32 v13, v13
	v_mul_f32_e32 v37, 0xbfb8aa3b, v37
	v_mul_f32_e32 v38, 0xbfb8aa3b, v38
	v_rcp_f32_e32 v36, v36
	v_exp_f32_e32 v21, v21
	v_exp_f32_e32 v37, v37
	v_exp_f32_e32 v38, v38
	v_rcp_f32_e32 v35, v32
	v_add_f32_e32 v32, 1.0, v33
	v_rcp_f32_e32 v40, v32
	v_add_f32_e32 v32, 1.0, v34
	v_add_f32_e32 v20, 1.0, v20
	v_rcp_f32_e32 v41, v32
	v_cvt_pk_bf16_f32 v32, v13, v36
	v_mul_f32_e32 v13, s50, v28
	v_mul_f32_e32 v28, s50, v29
	v_mul_f32_e32 v29, s50, v30
	v_mul_f32_e32 v30, s50, v31
	v_rcp_f32_e32 v31, v20
	v_add_f32_e32 v20, 1.0, v21
	v_mul_f32_e32 v21, s50, v22
	v_add_f32_e32 v37, 1.0, v37
	v_add_f32_e32 v38, 1.0, v38
	v_mul_f32_e32 v21, 0xbfb8aa3b, v21
	v_mul_f32_e32 v22, s50, v23
	v_rcp_f32_e32 v37, v37
	v_rcp_f32_e32 v38, v38
	v_mul_f32_e32 v13, 0xbfb8aa3b, v13
	v_mul_f32_e32 v28, 0xbfb8aa3b, v28
	v_mul_f32_e32 v29, 0xbfb8aa3b, v29
	v_mul_f32_e32 v30, 0xbfb8aa3b, v30
	v_exp_f32_e32 v21, v21
	v_mul_f32_e32 v22, 0xbfb8aa3b, v22
	v_exp_f32_e32 v13, v13
	v_exp_f32_e32 v28, v28
	v_exp_f32_e32 v29, v29
	v_exp_f32_e32 v30, v30
	v_exp_f32_e32 v22, v22
	v_lshl_add_u64 v[14:15], v[14:15], 0, v[4:5]
	v_cvt_pk_bf16_f32 v33, v37, v38
	v_cvt_pk_bf16_f32 v34, v39, v35
	v_cvt_pk_bf16_f32 v35, v40, v41
	v_rcp_f32_e32 v23, v20
	v_add_f32_e32 v20, 1.0, v21
	global_store_dwordx4 v[14:15], v[32:35], off sc1
	v_add_f32_e32 v13, 1.0, v13
	v_add_f32_e32 v28, 1.0, v28
	v_add_f32_e32 v29, 1.0, v29
	v_add_f32_e32 v30, 1.0, v30
	v_rcp_f32_e32 v32, v20
	v_add_f32_e32 v20, 1.0, v22
	v_rcp_f32_e32 v13, v13
	v_rcp_f32_e32 v28, v28
	v_rcp_f32_e32 v29, v29
	v_rcp_f32_e32 v30, v30
	v_rcp_f32_e32 v33, v20
	v_cvt_pk_bf16_f32 v20, v13, v28
	v_cvt_pk_bf16_f32 v22, v31, v23
	v_cvt_pk_bf16_f32 v21, v29, v30
	v_cvt_pk_bf16_f32 v23, v32, v33
	global_store_dwordx4 v[14:15], v[20:23], off offset:256 sc1
	v_add_u32_e32 v12, 0xb0, v12
	v_mad_u64_u32 v[6:7], s[2:3], v12, s25, v[6:7]
	v_mul_f32_e32 v12, s50, v24
	v_mul_f32_e32 v12, 0xbfb8aa3b, v12
	v_exp_f32_e32 v14, v12
	v_mul_f32_e32 v12, s50, v25
	v_mul_f32_e32 v12, 0xbfb8aa3b, v12
	v_exp_f32_e32 v15, v12
	v_lshl_add_u64 v[12:13], v[6:7], 0, v[4:5]
	v_add_f32_e32 v4, 1.0, v14
	v_mul_f32_e32 v6, s50, v26
	v_add_f32_e32 v5, 1.0, v15
	v_mul_f32_e32 v7, s50, v27
	v_mul_f32_e32 v14, s50, v16
	v_mul_f32_e32 v15, s50, v17
	v_mul_f32_e32 v16, s50, v18
	v_mul_f32_e32 v17, s50, v19
	v_mul_f32_e32 v6, 0xbfb8aa3b, v6
	v_mul_f32_e32 v7, 0xbfb8aa3b, v7
	v_mul_f32_e32 v14, 0xbfb8aa3b, v14
	v_mul_f32_e32 v15, 0xbfb8aa3b, v15
	v_mul_f32_e32 v16, 0xbfb8aa3b, v16
	v_mul_f32_e32 v17, 0xbfb8aa3b, v17
	v_exp_f32_e32 v6, v6
	v_exp_f32_e32 v7, v7
	v_exp_f32_e32 v14, v14
	v_exp_f32_e32 v15, v15
	v_exp_f32_e32 v16, v16
	v_exp_f32_e32 v17, v17
	v_mul_f32_e32 v0, s50, v0
	v_add_f32_e32 v6, 1.0, v6
	v_add_f32_e32 v7, 1.0, v7
	v_add_f32_e32 v14, 1.0, v14
	v_add_f32_e32 v15, 1.0, v15
	v_add_f32_e32 v16, 1.0, v16
	v_add_f32_e32 v17, 1.0, v17
	v_mul_f32_e32 v8, s50, v8
	v_mul_f32_e32 v0, 0xbfb8aa3b, v0
	v_mul_f32_e32 v1, s50, v1
	v_rcp_f32_e32 v4, v4
	v_rcp_f32_e32 v5, v5
	v_rcp_f32_e32 v6, v6
	v_rcp_f32_e32 v7, v7
	v_rcp_f32_e32 v14, v14
	v_rcp_f32_e32 v15, v15
	v_rcp_f32_e32 v16, v16
	v_rcp_f32_e32 v17, v17
	v_mul_f32_e32 v8, 0xbfb8aa3b, v8
	v_exp_f32_e32 v0, v0
	v_mul_f32_e32 v1, 0xbfb8aa3b, v1
	v_exp_f32_e32 v8, v8
	v_exp_f32_e32 v1, v1
	v_cvt_pk_bf16_f32 v4, v4, v5
	v_cvt_pk_bf16_f32 v5, v6, v7
	v_cvt_pk_bf16_f32 v6, v14, v15
	v_cvt_pk_bf16_f32 v7, v16, v17
	v_add_f32_e32 v0, 1.0, v0
	global_store_dwordx4 v[12:13], v[4:7], off sc1
	v_mul_f32_e32 v9, s50, v9
	v_mul_f32_e32 v9, 0xbfb8aa3b, v9
	v_add_f32_e32 v4, 1.0, v8
	v_rcp_f32_e32 v8, v0
	v_add_f32_e32 v0, 1.0, v1
	v_mul_f32_e32 v1, s50, v2
	v_mul_f32_e32 v6, s50, v10
	v_mul_f32_e32 v7, s50, v11
	v_mul_f32_e32 v1, 0xbfb8aa3b, v1
	v_mul_f32_e32 v2, s50, v3
	v_mul_f32_e32 v6, 0xbfb8aa3b, v6
	v_mul_f32_e32 v7, 0xbfb8aa3b, v7
	v_exp_f32_e32 v1, v1
	v_mul_f32_e32 v2, 0xbfb8aa3b, v2
	v_exp_f32_e32 v9, v9
	v_exp_f32_e32 v6, v6
	v_exp_f32_e32 v7, v7
	v_exp_f32_e32 v2, v2
	v_rcp_f32_e32 v3, v0
	v_add_f32_e32 v0, 1.0, v1
	v_add_f32_e32 v5, 1.0, v9
	v_add_f32_e32 v6, 1.0, v6
	v_add_f32_e32 v7, 1.0, v7
	v_rcp_f32_e32 v9, v0
	v_add_f32_e32 v0, 1.0, v2
	v_rcp_f32_e32 v4, v4
	v_rcp_f32_e32 v5, v5
	v_rcp_f32_e32 v6, v6
	v_rcp_f32_e32 v7, v7
	v_rcp_f32_e32 v10, v0
	v_cvt_pk_bf16_f32 v0, v4, v5
	v_cvt_pk_bf16_f32 v2, v8, v3
	v_cvt_pk_bf16_f32 v1, v6, v7
	v_cvt_pk_bf16_f32 v3, v9, v10
	s_andn2_b64 vcc, exec, s[30:31]
	s_mov_b64 s[4:5], -1
	global_store_dwordx4 v[12:13], v[0:3], off offset:256 sc1
	s_cbranch_vccnz .LBB0_464
	s_andn2_b64 vcc, exec, s[20:21]
	s_cbranch_vccnz .LBB0_463
	s_barrier
	s_branch .LBB0_463

.LBB0_534:
	v_div_scale_f32 v0, s[0:1], v119, v119, 1.0
	v_rcp_f32_e32 v66, v0
	s_waitcnt vmcnt(0) lgkmcnt(0)
	s_barrier
	v_fma_f32 v67, -v0, v66, 1.0
	v_fmac_f32_e32 v66, v67, v66
	v_div_scale_f32 v67, vcc, 1.0, v119, 1.0
	v_mul_f32_e32 v68, v67, v66
	v_fma_f32 v69, -v0, v68, v67
	v_fmac_f32_e32 v68, v69, v66
	v_fma_f32 v0, -v0, v68, v67
	v_div_fmas_f32 v0, v0, v66, v68
	v_div_fixup_f32 v0, v0, v119, 1.0
	v_add3_u32 v66, s71, v125, v118
	v_pk_mul_f32 v[50:51], v[50:51], v[0:1] op_sel_hi:[1,0]
	v_pk_mul_f32 v[52:53], v[52:53], v[0:1] op_sel_hi:[1,0]
	v_lshlrev_b32_e32 v67, 4, v121
	v_cvt_pk_bf16_f32 v50, v50, v51
	v_cvt_pk_bf16_f32 v51, v52, v53
	v_add_u32_e32 v52, v66, v67
	ds_write_b64 v52, v[50:51]
	v_pk_mul_f32 v[50:51], v[54:55], v[0:1] op_sel_hi:[1,0]
	v_pk_mul_f32 v[52:53], v[56:57], v[0:1] op_sel_hi:[1,0]
	v_cvt_pk_bf16_f32 v50, v50, v51
	v_cvt_pk_bf16_f32 v51, v52, v53
	v_xad_u32 v52, v67, 16, v66
	ds_write_b64 v52, v[50:51]
	v_pk_mul_f32 v[50:51], v[58:59], v[0:1] op_sel_hi:[1,0]
	v_pk_mul_f32 v[52:53], v[60:61], v[0:1] op_sel_hi:[1,0]
	v_cvt_pk_bf16_f32 v50, v50, v51
	v_cvt_pk_bf16_f32 v51, v52, v53
	v_xad_u32 v52, v67, 32, v66
	ds_write_b64 v52, v[50:51]
	v_pk_mul_f32 v[50:51], v[62:63], v[0:1] op_sel_hi:[1,0]
	v_pk_mul_f32 v[52:53], v[64:65], v[0:1] op_sel_hi:[1,0]
	v_pk_mul_f32 v[34:35], v[34:35], v[0:1] op_sel_hi:[1,0]
	v_pk_mul_f32 v[36:37], v[36:37], v[0:1] op_sel_hi:[1,0]
	v_cvt_pk_bf16_f32 v50, v50, v51
	v_cvt_pk_bf16_f32 v51, v52, v53
	v_xad_u32 v52, v67, 48, v66
	v_cvt_pk_bf16_f32 v34, v34, v35
	v_cvt_pk_bf16_f32 v35, v36, v37
	v_xad_u32 v36, v67, 64, v66
	ds_write_b64 v52, v[50:51]
	ds_write_b64 v36, v[34:35]
	v_pk_mul_f32 v[34:35], v[38:39], v[0:1] op_sel_hi:[1,0]
	v_pk_mul_f32 v[36:37], v[40:41], v[0:1] op_sel_hi:[1,0]
	s_movk_i32 s0, 0x50
	v_cvt_pk_bf16_f32 v34, v34, v35
	v_cvt_pk_bf16_f32 v35, v36, v37
	v_xad_u32 v36, v67, s0, v66
	ds_write_b64 v36, v[34:35]
	v_pk_mul_f32 v[34:35], v[42:43], v[0:1] op_sel_hi:[1,0]
	v_pk_mul_f32 v[36:37], v[44:45], v[0:1] op_sel_hi:[1,0]
	s_movk_i32 s0, 0x60
	v_cvt_pk_bf16_f32 v34, v34, v35
	v_cvt_pk_bf16_f32 v35, v36, v37
	v_xad_u32 v36, v67, s0, v66
	ds_write_b64 v36, v[34:35]
	v_pk_mul_f32 v[34:35], v[46:47], v[0:1] op_sel_hi:[1,0]
	v_pk_mul_f32 v[36:37], v[48:49], v[0:1] op_sel_hi:[1,0]
	s_movk_i32 s0, 0x70
	v_cvt_pk_bf16_f32 v34, v34, v35
	v_cvt_pk_bf16_f32 v35, v36, v37
	v_xad_u32 v36, v67, s0, v66
	v_pk_mul_f32 v[18:19], v[18:19], v[0:1] op_sel_hi:[1,0]
	v_pk_mul_f32 v[20:21], v[20:21], v[0:1] op_sel_hi:[1,0]
	s_movk_i32 s0, 0x80
	v_cvt_pk_bf16_f32 v18, v18, v19
	v_cvt_pk_bf16_f32 v19, v20, v21
	v_xad_u32 v20, v67, s0, v66
	ds_write_b64 v36, v[34:35]
	ds_write_b64 v20, v[18:19]
	v_pk_mul_f32 v[18:19], v[22:23], v[0:1] op_sel_hi:[1,0]
	v_pk_mul_f32 v[20:21], v[24:25], v[0:1] op_sel_hi:[1,0]
	s_movk_i32 s0, 0x90
	v_cvt_pk_bf16_f32 v18, v18, v19
	v_cvt_pk_bf16_f32 v19, v20, v21
	v_xad_u32 v20, v67, s0, v66
	ds_write_b64 v20, v[18:19]
	v_pk_mul_f32 v[18:19], v[26:27], v[0:1] op_sel_hi:[1,0]
	v_pk_mul_f32 v[20:21], v[28:29], v[0:1] op_sel_hi:[1,0]
	s_movk_i32 s0, 0xa0
	v_cvt_pk_bf16_f32 v18, v18, v19
	v_cvt_pk_bf16_f32 v19, v20, v21
	v_xad_u32 v20, v67, s0, v66
	ds_write_b64 v20, v[18:19]
	v_pk_mul_f32 v[18:19], v[30:31], v[0:1] op_sel_hi:[1,0]
	v_pk_mul_f32 v[20:21], v[32:33], v[0:1] op_sel_hi:[1,0]
	s_movk_i32 s0, 0xb0
	v_cvt_pk_bf16_f32 v18, v18, v19
	v_cvt_pk_bf16_f32 v19, v20, v21
	v_xad_u32 v20, v67, s0, v66
	v_pk_mul_f32 v[2:3], v[2:3], v[0:1] op_sel_hi:[1,0]
	v_pk_mul_f32 v[4:5], v[4:5], v[0:1] op_sel_hi:[1,0]
	s_movk_i32 s0, 0xc0
	v_cvt_pk_bf16_f32 v2, v2, v3
	v_cvt_pk_bf16_f32 v3, v4, v5
	v_xad_u32 v4, v67, s0, v66
	ds_write_b64 v20, v[18:19]
	ds_write_b64 v4, v[2:3]
	v_pk_mul_f32 v[2:3], v[6:7], v[0:1] op_sel_hi:[1,0]
	v_pk_mul_f32 v[4:5], v[8:9], v[0:1] op_sel_hi:[1,0]
	s_movk_i32 s0, 0xd0
	v_cvt_pk_bf16_f32 v2, v2, v3
	v_cvt_pk_bf16_f32 v3, v4, v5
	v_xad_u32 v4, v67, s0, v66
	ds_write_b64 v4, v[2:3]
	v_pk_mul_f32 v[2:3], v[10:11], v[0:1] op_sel_hi:[1,0]
	v_pk_mul_f32 v[4:5], v[12:13], v[0:1] op_sel_hi:[1,0]
	s_movk_i32 s0, 0xe0
	v_cvt_pk_bf16_f32 v2, v2, v3
	v_cvt_pk_bf16_f32 v3, v4, v5
	v_xad_u32 v4, v67, s0, v66
	s_movk_i32 s0, 0xf0
	ds_write_b64 v4, v[2:3]
	v_pk_mul_f32 v[2:3], v[14:15], v[0:1] op_sel_hi:[1,0]
	v_pk_mul_f32 v[4:5], v[16:17], v[0:1] op_sel_hi:[1,0]
	v_xad_u32 v0, v67, s0, v66
	v_readlane_b32 s0, v254, 55
	v_readlane_b32 s1, v254, 56
	v_cvt_pk_bf16_f32 v2, v2, v3
	v_cvt_pk_bf16_f32 v3, v4, v5
	s_lshl_b64 s[0:1], s[0:1], 1
	v_readlane_b32 s2, v255, 7
	ds_write_b64 v0, v[2:3]
	s_add_u32 s2, s2, s0
	v_readlane_b32 s0, v255, 8
	s_mov_b32 s87, s83
	v_lshlrev_b32_e32 v0, 4, v152
	s_addc_u32 s4, s0, s1
	s_lshl_b64 s[0:1], s[86:87], 11
	v_and_b32_e32 v0, 0xf0, v0
	s_add_u32 s0, s2, s0
	v_add_u32_e32 v14, s71, v0
	s_waitcnt lgkmcnt(0)
	s_addc_u32 s1, s4, s1
	s_lshl_b32 s2, s77, 1
	v_lshl_add_u32 v0, v114, 8, v14
	s_add_u32 s0, s0, s2
	ds_read_b128 v[2:5], v0
	v_ashrrev_i32_e32 v115, 31, v114
	s_addc_u32 s1, s1, 0
	v_lshlrev_b64 v[6:7], 11, v[114:115]
	v_lshl_add_u64 v[6:7], s[0:1], 0, v[6:7]
	v_lshlrev_b32_e32 v0, 1, v116
	v_add_u32_e32 v12, 4, v114
	v_lshl_add_u64 v[10:11], v[6:7], 0, v[0:1]
	v_lshl_add_u32 v6, v12, 8, v14
	ds_read_b128 v[6:9], v6
	s_waitcnt lgkmcnt(1)
	global_store_dwordx4 v[10:11], v[2:5], off sc1
	v_ashrrev_i32_e32 v13, 31, v12
	v_cmp_gt_u32_e32 vcc, 32, v152
	v_xor_b32_e32 v4, v12, v152
	v_lshlrev_b64 v[2:3], 11, v[12:13]
	v_lshlrev_b32_e32 v4, 4, v4
	v_lshl_add_u64 v[2:3], s[0:1], 0, v[2:3]
	v_and_b32_e32 v4, 0xf0, v4
	v_mov_b32_e32 v5, v1
	v_lshl_add_u64 v[2:3], v[2:3], 0, v[4:5]
	s_waitcnt lgkmcnt(0)
	global_store_dwordx4 v[2:3], v[6:9], off sc1
	v_add_u32_e32 v12, 12, v114
	v_ashrrev_i32_e32 v13, 31, v12
	v_add_u32_e32 v6, 8, v114
	v_lshl_add_u32 v2, v6, 8, v14
	v_xor_b32_e32 v8, v6, v152
	ds_read_b128 v[2:5], v2
	v_ashrrev_i32_e32 v7, 31, v6
	v_lshlrev_b64 v[6:7], 11, v[6:7]
	v_lshlrev_b32_e32 v8, 4, v8
	v_lshl_add_u64 v[6:7], s[0:1], 0, v[6:7]
	v_and_b32_e32 v8, 0xf0, v8
	v_mov_b32_e32 v9, v1
	v_lshl_add_u64 v[10:11], v[6:7], 0, v[8:9]
	v_lshl_add_u32 v6, v12, 8, v14
	ds_read_b128 v[6:9], v6
	s_waitcnt lgkmcnt(1)
	global_store_dwordx4 v[10:11], v[2:5], off sc1
	s_nop 1
	v_xor_b32_e32 v4, v12, v152
	v_lshlrev_b64 v[2:3], 11, v[12:13]
	v_lshlrev_b32_e32 v4, 4, v4
	v_lshl_add_u64 v[2:3], s[0:1], 0, v[2:3]
	v_and_b32_e32 v4, 0xf0, v4
	v_mov_b32_e32 v5, v1
	v_lshl_add_u64 v[2:3], v[2:3], 0, v[4:5]
	s_waitcnt lgkmcnt(0)
	global_store_dwordx4 v[2:3], v[6:9], off sc1
	v_add_u32_e32 v12, 20, v114
	v_ashrrev_i32_e32 v13, 31, v12
	v_add_u32_e32 v6, 16, v114
	v_lshl_add_u32 v2, v6, 8, v14
	v_ashrrev_i32_e32 v7, 31, v6
	ds_read_b128 v[2:5], v2
	v_lshlrev_b64 v[6:7], 11, v[6:7]
	v_lshl_add_u64 v[6:7], s[0:1], 0, v[6:7]
	v_lshl_add_u64 v[10:11], v[6:7], 0, v[0:1]
	v_lshl_add_u32 v0, v12, 8, v14
	ds_read_b128 v[6:9], v0
	v_xor_b32_e32 v0, v12, v152
	s_waitcnt lgkmcnt(1)
	global_store_dwordx4 v[10:11], v[2:5], off sc1
	v_lshlrev_b32_e32 v0, 4, v0
	v_and_b32_e32 v0, 0xf0, v0
	v_lshlrev_b64 v[2:3], 11, v[12:13]
	v_lshl_add_u64 v[2:3], s[0:1], 0, v[2:3]
	v_lshl_add_u64 v[2:3], v[2:3], 0, v[0:1]
	s_waitcnt lgkmcnt(0)
	global_store_dwordx4 v[2:3], v[6:9], off sc1
	v_add_u32_e32 v12, 28, v114
	v_ashrrev_i32_e32 v13, 31, v12
	v_add_u32_e32 v6, 24, v114
	v_xor_b32_e32 v0, v6, v152
	v_lshl_add_u32 v2, v6, 8, v14
	v_ashrrev_i32_e32 v7, 31, v6
	ds_read_b128 v[2:5], v2
	v_lshlrev_b64 v[6:7], 11, v[6:7]
	v_lshlrev_b32_e32 v0, 4, v0
	v_lshl_add_u64 v[6:7], s[0:1], 0, v[6:7]
	v_and_b32_e32 v0, 0xf0, v0
	v_lshl_add_u64 v[10:11], v[6:7], 0, v[0:1]
	v_lshl_add_u32 v0, v12, 8, v14
	ds_read_b128 v[6:9], v0
	v_xor_b32_e32 v0, v12, v152
	s_waitcnt lgkmcnt(1)
	global_store_dwordx4 v[10:11], v[2:5], off sc1
	v_lshlrev_b32_e32 v0, 4, v0
	v_and_b32_e32 v0, 0xf0, v0
	v_lshlrev_b64 v[2:3], 11, v[12:13]
	v_lshl_add_u64 v[2:3], s[0:1], 0, v[2:3]
	v_lshl_add_u64 v[2:3], v[2:3], 0, v[0:1]
	s_waitcnt lgkmcnt(0)
	global_store_dwordx4 v[2:3], v[6:9], off sc1
	s_and_saveexec_b64 s[0:1], vcc
	s_cbranch_execz .LBB0_517
	v_log_f32_e32 v2, v119
	s_lshl_b64 s[4:5], s[84:85], 19
	v_readlane_b32 s2, v255, 9
	v_or_b32_e32 v0, s86, v152
	s_add_u32 s4, s2, s4
	v_readlane_b32 s2, v255, 10
	v_add_f32_e32 v4, v160, v2
	s_addc_u32 s5, s2, s5
	v_lshlrev_b64 v[2:3], 5, v[0:1]
	v_lshl_add_u64 v[2:3], s[4:5], 0, v[2:3]
	s_lshl_b32 s82, s72, 2
	v_lshl_add_u64 v[2:3], v[2:3], 0, s[82:83]
	global_store_dword v[2:3], v4, off sc1
	s_branch .LBB0_517

.LBB0_595:
	s_or_b64 exec, exec, s[0:1]
	s_lshl_b32 s0, s83, 2
	s_add_u32 s0, s45, s0
	v_lshlrev_b32_e32 v130, 2, v139
	v_lshlrev_b32_e32 v128, 3, v134
	s_addc_u32 s1, s46, 0
	v_ashrrev_i32_e32 v131, 31, v130
	v_and_b32_e32 v140, 56, v128
	v_mul_u32_u24_e32 v128, 0x110, v138
	v_lshlrev_b32_e32 v139, 4, v139
	v_lshl_add_u64 v[130:131], v[130:131], 2, s[0:1]
	s_add_u32 s0, s83, s20
	v_add3_u32 v128, s47, v128, v139
	v_lshl_add_u32 v139, v138, 6, 0
	s_waitcnt lgkmcnt(0)
	s_barrier
	v_ashrrev_i32_e32 v133, 3, v134
	v_or_b32_e32 v134, s0, v140
	v_lshlrev_b32_e32 v160, 2, v140
	ds_read_b128 v[140:143], v139 offset:20480
	ds_read_b128 v[144:147], v139 offset:20496
	global_load_dwordx4 v[148:151], v[130:131], off
	ds_read_b128 v[152:155], v139 offset:20512
	ds_read_b128 v[156:159], v139 offset:20528
	v_add_u32_e32 v132, s28, v133
	s_waitcnt lgkmcnt(3)
	v_pk_add_f32 v[140:141], v[140:141], 0 op_sel_hi:[1,0]
	v_mul_lo_u32 v133, v133, s66
	v_pk_add_f32 v[140:141], v[140:141], v[142:143]
	s_addc_u32 s1, 0, s21
	s_waitcnt lgkmcnt(2)
	v_pk_add_f32 v[140:141], v[140:141], v[144:145]
	v_mov_b32_e32 v135, s1
	v_pk_add_f32 v[144:145], v[140:141], v[146:147]
	global_load_dwordx4 v[140:143], v[130:131], off offset:32
	s_waitcnt lgkmcnt(1)
	v_pk_add_f32 v[144:145], v[144:145], v[152:153]
	s_nop 0
	v_pk_add_f32 v[144:145], v[144:145], v[154:155]
	s_waitcnt lgkmcnt(0)
	v_pk_add_f32 v[144:145], v[144:145], v[156:157]
	s_nop 0
	v_pk_add_f32 v[144:145], v[144:145], v[158:159]
	s_nop 0
	v_pk_mul_f32 v[188:189], v[144:145], s[26:27] op_sel_hi:[1,0]
	global_load_dwordx4 v[144:147], v[130:131], off offset:64
	v_fma_f32 v138, -v188, v188, v189
	v_max_f32_e32 v138, 0, v138
	v_add_f32_e32 v138, 0x358637bd, v138
	v_mul_f32_e32 v152, 0x4f800000, v138
	v_cmp_gt_f32_e32 vcc, s67, v138
	v_pk_add_f32 v[112:113], v[112:113], v[188:189] op_sel_hi:[1,0] neg_lo:[0,1] neg_hi:[0,1]
	v_pk_add_f32 v[114:115], v[114:115], v[188:189] op_sel_hi:[1,0] neg_lo:[0,1] neg_hi:[0,1]
	v_cndmask_b32_e32 v164, v138, v152, vcc
	v_sqrt_f32_e32 v161, v164
	v_add3_u32 v138, s47, v160, v133
	global_load_dwordx4 v[152:155], v[130:131], off offset:96
	v_pk_add_f32 v[96:97], v[96:97], v[188:189] op_sel_hi:[1,0] neg_lo:[0,1] neg_hi:[0,1]
	v_add_u32_e32 v133, -1, v161
	v_fma_f32 v156, -v133, v161, v164
	v_cmp_ge_f32_e64 s[0:1], 0, v156
	v_add_u32_e32 v160, 1, v161
	global_load_dwordx4 v[156:159], v[130:131], off offset:128
	v_cndmask_b32_e64 v133, v161, v133, s[0:1]
	v_fma_f32 v161, -v160, v161, v164
	v_cmp_lt_f32_e64 s[0:1], 0, v161
	v_pk_add_f32 v[98:99], v[98:99], v[188:189] op_sel_hi:[1,0] neg_lo:[0,1] neg_hi:[0,1]
	s_nop 0
	v_cndmask_b32_e64 v133, v133, v160, s[0:1]
	v_mul_f32_e32 v160, 0x37800000, v133
	v_cndmask_b32_e32 v133, v133, v160, vcc
	v_cmp_class_f32_e32 vcc, v164, v136
	global_load_dwordx4 v[160:163], v[130:131], off offset:160
	s_nop 0
	v_cndmask_b32_e32 v192, v133, v164, vcc
	v_ashrrev_i32_e32 v133, 31, v132
	v_lshlrev_b64 v[164:165], 12, v[132:133]
	v_lshl_add_u64 v[164:165], v[134:135], 0, v[164:165]
	v_lshlrev_b64 v[190:191], 1, v[164:165]
	global_load_dwordx4 v[164:167], v[130:131], off offset:192
	v_lshl_add_u64 v[180:181], s[22:23], 0, v[190:191]
	v_add_co_u32_e32 v176, vcc, s73, v180
	v_div_scale_f32 v133, s[0:1], v192, v192, 1.0
	s_nop 0
	v_addc_co_u32_e32 v177, vcc, 0, v181, vcc
	global_load_dwordx4 v[168:171], v[130:131], off offset:224
	global_load_dwordx4 v[172:175], v[180:181], off nt
	s_nop 0
	global_load_dwordx4 v[176:179], v[176:177], off nt
	v_add_co_u32_e32 v182, vcc, s78, v180
	v_rcp_f32_e32 v193, v133
	s_nop 0
	v_addc_co_u32_e32 v183, vcc, 0, v181, vcc
	v_add_co_u32_e32 v184, vcc, 0x30000, v180
	v_fma_f32 v194, -v133, v193, 1.0
	s_nop 0
	v_addc_co_u32_e32 v185, vcc, 0, v181, vcc
	global_load_dwordx4 v[180:183], v[182:183], off nt
	s_nop 0
	global_load_dwordx4 v[184:187], v[184:185], off nt
	v_fmac_f32_e32 v193, v194, v193
	v_div_scale_f32 v194, vcc, 1.0, v192, 1.0
	v_mul_f32_e32 v195, v194, v193
	v_fma_f32 v196, -v133, v195, v194
	v_fmac_f32_e32 v195, v196, v193
	v_fma_f32 v133, -v133, v195, v194
	v_div_fmas_f32 v133, v133, v193, v195
	v_div_fixup_f32 v192, v133, v192, 1.0
	v_pk_mul_f32 v[112:113], v[112:113], v[192:193] op_sel_hi:[1,0]
	v_pk_mul_f32 v[114:115], v[114:115], v[192:193] op_sel_hi:[1,0]
	v_pk_mul_f32 v[96:97], v[96:97], v[192:193] op_sel_hi:[1,0]
	v_pk_mul_f32 v[98:99], v[98:99], v[192:193] op_sel_hi:[1,0]
	s_waitcnt vmcnt(11)
	v_pk_mul_f32 v[112:113], v[148:149], v[112:113]
	v_pk_mul_f32 v[114:115], v[150:151], v[114:115]
	ds_write_b128 v128, v[112:115] offset:32768
	v_pk_add_f32 v[112:113], v[116:117], v[188:189] op_sel_hi:[1,0] neg_lo:[0,1] neg_hi:[0,1]
	v_pk_add_f32 v[114:115], v[118:119], v[188:189] op_sel_hi:[1,0] neg_lo:[0,1] neg_hi:[0,1]
	v_pk_mul_f32 v[112:113], v[112:113], v[192:193] op_sel_hi:[1,0]
	v_pk_mul_f32 v[114:115], v[114:115], v[192:193] op_sel_hi:[1,0]
	s_waitcnt vmcnt(10)
	v_pk_mul_f32 v[112:113], v[140:141], v[112:113]
	v_pk_mul_f32 v[114:115], v[142:143], v[114:115]
	ds_write_b128 v128, v[112:115] offset:32800
	v_pk_add_f32 v[112:113], v[120:121], v[188:189] op_sel_hi:[1,0] neg_lo:[0,1] neg_hi:[0,1]
	v_pk_add_f32 v[114:115], v[122:123], v[188:189] op_sel_hi:[1,0] neg_lo:[0,1] neg_hi:[0,1]
	v_pk_mul_f32 v[112:113], v[112:113], v[192:193] op_sel_hi:[1,0]
	v_pk_mul_f32 v[114:115], v[114:115], v[192:193] op_sel_hi:[1,0]
	s_waitcnt vmcnt(9)
	v_pk_mul_f32 v[112:113], v[112:113], v[144:145]
	v_pk_mul_f32 v[114:115], v[114:115], v[146:147]
	ds_write_b128 v128, v[112:115] offset:32832
	v_pk_add_f32 v[112:113], v[124:125], v[188:189] op_sel_hi:[1,0] neg_lo:[0,1] neg_hi:[0,1]
	v_pk_add_f32 v[114:115], v[126:127], v[188:189] op_sel_hi:[1,0] neg_lo:[0,1] neg_hi:[0,1]
	v_pk_mul_f32 v[112:113], v[112:113], v[192:193] op_sel_hi:[1,0]
	v_pk_mul_f32 v[114:115], v[114:115], v[192:193] op_sel_hi:[1,0]
	s_waitcnt vmcnt(8)
	v_pk_mul_f32 v[112:113], v[112:113], v[152:153]
	v_pk_mul_f32 v[114:115], v[114:115], v[154:155]
	ds_write_b128 v128, v[112:115] offset:32864
	s_waitcnt vmcnt(7)
	v_pk_mul_f32 v[96:97], v[96:97], v[156:157]
	v_pk_mul_f32 v[98:99], v[98:99], v[158:159]
	ds_write_b128 v128, v[96:99] offset:32896
	v_pk_add_f32 v[96:97], v[100:101], v[188:189] op_sel_hi:[1,0] neg_lo:[0,1] neg_hi:[0,1]
	v_pk_add_f32 v[98:99], v[102:103], v[188:189] op_sel_hi:[1,0] neg_lo:[0,1] neg_hi:[0,1]
	v_pk_mul_f32 v[96:97], v[96:97], v[192:193] op_sel_hi:[1,0]
	v_pk_mul_f32 v[98:99], v[98:99], v[192:193] op_sel_hi:[1,0]
	s_waitcnt vmcnt(6)
	v_pk_mul_f32 v[96:97], v[96:97], v[160:161]
	v_pk_mul_f32 v[98:99], v[98:99], v[162:163]
	ds_write_b128 v128, v[96:99] offset:32928
	v_pk_add_f32 v[96:97], v[104:105], v[188:189] op_sel_hi:[1,0] neg_lo:[0,1] neg_hi:[0,1]
	v_pk_add_f32 v[98:99], v[106:107], v[188:189] op_sel_hi:[1,0] neg_lo:[0,1] neg_hi:[0,1]
	v_pk_mul_f32 v[96:97], v[96:97], v[192:193] op_sel_hi:[1,0]
	v_pk_mul_f32 v[98:99], v[98:99], v[192:193] op_sel_hi:[1,0]
	s_waitcnt vmcnt(5)
	v_pk_mul_f32 v[96:97], v[96:97], v[164:165]
	v_pk_mul_f32 v[98:99], v[98:99], v[166:167]
	ds_write_b128 v128, v[96:99] offset:32960
	v_pk_add_f32 v[96:97], v[108:109], v[188:189] op_sel_hi:[1,0] neg_lo:[0,1] neg_hi:[0,1]
	v_pk_add_f32 v[98:99], v[110:111], v[188:189] op_sel_hi:[1,0] neg_lo:[0,1] neg_hi:[0,1]
	v_pk_mul_f32 v[96:97], v[96:97], v[192:193] op_sel_hi:[1,0]
	v_pk_mul_f32 v[98:99], v[98:99], v[192:193] op_sel_hi:[1,0]
	s_waitcnt vmcnt(4)
	v_pk_mul_f32 v[96:97], v[96:97], v[168:169]
	v_pk_mul_f32 v[98:99], v[98:99], v[170:171]
	ds_write_b128 v128, v[96:99] offset:32992
	s_waitcnt lgkmcnt(0)
	ds_read_b128 v[96:99], v138 offset:32768
	ds_read_b128 v[100:103], v138 offset:32784
	s_waitcnt vmcnt(3)
	v_lshlrev_b32_e32 v106, 16, v172
	v_and_b32_e32 v107, 0xffff0000, v172
	v_lshlrev_b32_e32 v108, 16, v173
	v_and_b32_e32 v109, 0xffff0000, v173
	v_lshlrev_b32_e32 v110, 16, v174
	v_and_b32_e32 v111, 0xffff0000, v174
	v_lshlrev_b32_e32 v112, 16, v175
	v_and_b32_e32 v113, 0xffff0000, v175
	s_waitcnt lgkmcnt(1)
	v_pk_mul_f32 v[98:99], v[98:99], v[108:109]
	v_pk_mul_f32 v[96:97], v[96:97], v[106:107]
	s_waitcnt lgkmcnt(0)
	v_pk_mul_f32 v[102:103], v[102:103], v[112:113]
	v_pk_mul_f32 v[100:101], v[100:101], v[110:111]
	v_lshl_add_u64 v[104:105], s[24:25], 0, v[190:191]
	v_cvt_pk_bf16_f32 v96, v96, v97
	v_cvt_pk_bf16_f32 v97, v98, v99
	v_cvt_pk_bf16_f32 v98, v100, v101
	v_cvt_pk_bf16_f32 v99, v102, v103
	global_store_dwordx4 v[104:105], v[96:99], off sc1
	ds_read_b128 v[96:99], v138 offset:34944
	ds_read_b128 v[100:103], v138 offset:34960
	s_waitcnt vmcnt(3)
	v_lshlrev_b32_e32 v106, 16, v176
	v_and_b32_e32 v107, 0xffff0000, v176
	v_lshlrev_b32_e32 v108, 16, v177
	v_and_b32_e32 v109, 0xffff0000, v177
	v_lshlrev_b32_e32 v110, 16, v178
	v_and_b32_e32 v111, 0xffff0000, v178
	v_lshlrev_b32_e32 v112, 16, v179
	v_and_b32_e32 v113, 0xffff0000, v179
	s_waitcnt lgkmcnt(1)
	v_pk_mul_f32 v[98:99], v[98:99], v[108:109]
	v_pk_mul_f32 v[96:97], v[96:97], v[106:107]
	s_waitcnt lgkmcnt(0)
	v_pk_mul_f32 v[100:101], v[100:101], v[110:111]
	v_pk_mul_f32 v[102:103], v[102:103], v[112:113]
	v_cvt_pk_bf16_f32 v96, v96, v97
	v_cvt_pk_bf16_f32 v97, v98, v99
	v_cvt_pk_bf16_f32 v98, v100, v101
	v_add_co_u32_e32 v100, vcc, s73, v104
	v_cvt_pk_bf16_f32 v99, v102, v103
	s_nop 0
	v_addc_co_u32_e32 v101, vcc, 0, v105, vcc
	global_store_dwordx4 v[100:101], v[96:99], off sc1
	ds_read_b128 v[96:99], v138 offset:37120
	ds_read_b128 v[100:103], v138 offset:37136
	s_waitcnt vmcnt(3)
	v_lshlrev_b32_e32 v106, 16, v180
	v_and_b32_e32 v107, 0xffff0000, v180
	v_lshlrev_b32_e32 v108, 16, v181
	v_and_b32_e32 v109, 0xffff0000, v181
	v_lshlrev_b32_e32 v110, 16, v182
	v_and_b32_e32 v111, 0xffff0000, v182
	v_lshlrev_b32_e32 v112, 16, v183
	v_and_b32_e32 v113, 0xffff0000, v183
	s_waitcnt lgkmcnt(1)
	v_pk_mul_f32 v[98:99], v[98:99], v[108:109]
	v_pk_mul_f32 v[96:97], v[96:97], v[106:107]
	s_waitcnt lgkmcnt(0)
	v_pk_mul_f32 v[100:101], v[100:101], v[110:111]
	v_pk_mul_f32 v[102:103], v[102:103], v[112:113]
	v_cvt_pk_bf16_f32 v96, v96, v97
	v_cvt_pk_bf16_f32 v97, v98, v99
	v_cvt_pk_bf16_f32 v98, v100, v101
	v_add_co_u32_e32 v100, vcc, s78, v104
	v_cvt_pk_bf16_f32 v99, v102, v103
	s_nop 0
	v_addc_co_u32_e32 v101, vcc, 0, v105, vcc
	global_store_dwordx4 v[100:101], v[96:99], off sc1
	ds_read_b128 v[96:99], v138 offset:39296
	ds_read_b128 v[100:103], v138 offset:39312
	s_waitcnt vmcnt(3)
	v_lshlrev_b32_e32 v106, 16, v184
	v_and_b32_e32 v107, 0xffff0000, v184
	v_lshlrev_b32_e32 v108, 16, v185
	v_and_b32_e32 v109, 0xffff0000, v185
	v_lshlrev_b32_e32 v110, 16, v186
	v_and_b32_e32 v111, 0xffff0000, v186
	v_lshlrev_b32_e32 v112, 16, v187
	v_and_b32_e32 v113, 0xffff0000, v187
	s_waitcnt lgkmcnt(1)
	v_pk_mul_f32 v[98:99], v[98:99], v[108:109]
	v_pk_mul_f32 v[96:97], v[96:97], v[106:107]
	s_waitcnt lgkmcnt(0)
	v_pk_mul_f32 v[100:101], v[100:101], v[110:111]
	v_pk_mul_f32 v[102:103], v[102:103], v[112:113]
	v_cvt_pk_bf16_f32 v96, v96, v97
	v_cvt_pk_bf16_f32 v97, v98, v99
	v_cvt_pk_bf16_f32 v98, v100, v101
	v_add_co_u32_e32 v100, vcc, s79, v104
	v_cvt_pk_bf16_f32 v99, v102, v103
	s_nop 0
	v_addc_co_u32_e32 v101, vcc, 0, v105, vcc
	global_store_dwordx4 v[100:101], v[96:99], off sc1
	s_waitcnt lgkmcnt(0)
	ds_read_b128 v[96:99], v139 offset:22528
	ds_read_b128 v[100:103], v139 offset:22544
	global_load_dwordx4 v[104:107], v[130:131], off
	ds_read_b128 v[108:111], v139 offset:22560
	ds_read_b128 v[112:115], v139 offset:22576
	s_waitcnt lgkmcnt(3)
	v_pk_add_f32 v[96:97], v[96:97], 0 op_sel_hi:[1,0]
	s_nop 0
	v_pk_add_f32 v[96:97], v[96:97], v[98:99]
	s_waitcnt lgkmcnt(2)
	v_pk_add_f32 v[96:97], v[96:97], v[100:101]
	s_nop 0
	v_pk_add_f32 v[96:97], v[96:97], v[102:103]
	s_waitcnt lgkmcnt(1)
	v_pk_add_f32 v[100:101], v[96:97], v[108:109]
	global_load_dwordx4 v[96:99], v[130:131], off offset:32
	v_pk_add_f32 v[100:101], v[100:101], v[110:111]
	s_waitcnt lgkmcnt(0)
	v_pk_add_f32 v[100:101], v[100:101], v[112:113]
	s_nop 0
	v_pk_add_f32 v[100:101], v[100:101], v[114:115]
	s_nop 0
	v_pk_mul_f32 v[156:157], v[100:101], s[26:27] op_sel_hi:[1,0]
	s_nop 0
	v_fma_f32 v100, -v156, v156, v157
	v_max_f32_e32 v108, 0, v100
	v_add_f32_e32 v108, 0x358637bd, v108
	v_mul_f32_e32 v109, 0x4f800000, v108
	v_cmp_gt_f32_e32 vcc, s67, v108
	global_load_dwordx4 v[100:103], v[130:131], off offset:64
	v_pk_add_f32 v[80:81], v[80:81], v[156:157] op_sel_hi:[1,0] neg_lo:[0,1] neg_hi:[0,1]
	v_cndmask_b32_e32 v120, v108, v109, vcc
	v_sqrt_f32_e32 v116, v120
	global_load_dwordx4 v[108:111], v[130:131], off offset:96
	v_pk_add_f32 v[82:83], v[82:83], v[156:157] op_sel_hi:[1,0] neg_lo:[0,1] neg_hi:[0,1]
	v_pk_add_f32 v[64:65], v[64:65], v[156:157] op_sel_hi:[1,0] neg_lo:[0,1] neg_hi:[0,1]
	v_add_u32_e32 v112, -1, v116
	v_fma_f32 v113, -v112, v116, v120
	v_cmp_ge_f32_e64 s[0:1], 0, v113
	v_add_u32_e32 v118, 1, v116
	v_pk_add_f32 v[66:67], v[66:67], v[156:157] op_sel_hi:[1,0] neg_lo:[0,1] neg_hi:[0,1]
	v_cndmask_b32_e64 v117, v116, v112, s[0:1]
	v_fma_f32 v116, -v118, v116, v120
	v_cmp_lt_f32_e64 s[0:1], 0, v116
	global_load_dwordx4 v[112:115], v[130:131], off offset:128
	s_nop 0
	v_cndmask_b32_e64 v116, v117, v118, s[0:1]
	v_mul_f32_e32 v117, 0x37800000, v116
	v_cndmask_b32_e32 v121, v116, v117, vcc
	v_cmp_class_f32_e32 vcc, v120, v136
	global_load_dwordx4 v[116:119], v[130:131], off offset:160
	s_nop 0
	v_cndmask_b32_e32 v133, v121, v120, vcc
	v_add_u32_e32 v120, 32, v132
	v_ashrrev_i32_e32 v121, 31, v120
	v_lshlrev_b64 v[120:121], 12, v[120:121]
	v_lshl_add_u64 v[120:121], v[120:121], 0, v[134:135]
	v_lshlrev_b64 v[158:159], 1, v[120:121]
	global_load_dwordx4 v[120:123], v[130:131], off offset:192
	v_lshl_add_u64 v[148:149], s[22:23], 0, v[158:159]
	v_add_co_u32_e32 v144, vcc, s73, v148
	v_div_scale_f32 v160, s[0:1], v133, v133, 1.0
	s_nop 0
	v_addc_co_u32_e32 v145, vcc, 0, v149, vcc
	global_load_dwordx4 v[124:127], v[130:131], off offset:224
	global_load_dwordx4 v[140:143], v[148:149], off nt
	s_nop 0
	global_load_dwordx4 v[144:147], v[144:145], off nt
	v_add_co_u32_e32 v150, vcc, s78, v148
	v_rcp_f32_e32 v161, v160
	s_nop 0
	v_addc_co_u32_e32 v151, vcc, 0, v149, vcc
	v_add_co_u32_e32 v152, vcc, 0x30000, v148
	v_fma_f32 v162, -v160, v161, 1.0
	s_nop 0
	v_addc_co_u32_e32 v153, vcc, 0, v149, vcc
	global_load_dwordx4 v[148:151], v[150:151], off nt
	s_nop 0
	global_load_dwordx4 v[152:155], v[152:153], off nt
	v_fmac_f32_e32 v161, v162, v161
	v_div_scale_f32 v162, vcc, 1.0, v133, 1.0
	v_mul_f32_e32 v163, v162, v161
	v_fma_f32 v164, -v160, v163, v162
	v_fmac_f32_e32 v163, v164, v161
	v_fma_f32 v160, -v160, v163, v162
	v_div_fmas_f32 v160, v160, v161, v163
	v_div_fixup_f32 v160, v160, v133, 1.0
	v_pk_mul_f32 v[80:81], v[80:81], v[160:161] op_sel_hi:[1,0]
	v_pk_mul_f32 v[82:83], v[82:83], v[160:161] op_sel_hi:[1,0]
	v_pk_mul_f32 v[64:65], v[64:65], v[160:161] op_sel_hi:[1,0]
	v_pk_mul_f32 v[66:67], v[66:67], v[160:161] op_sel_hi:[1,0]
	s_waitcnt vmcnt(11)
	v_pk_mul_f32 v[80:81], v[104:105], v[80:81]
	v_pk_mul_f32 v[82:83], v[106:107], v[82:83]
	ds_write_b128 v128, v[80:83] offset:32768
	v_pk_add_f32 v[80:81], v[84:85], v[156:157] op_sel_hi:[1,0] neg_lo:[0,1] neg_hi:[0,1]
	v_pk_add_f32 v[82:83], v[86:87], v[156:157] op_sel_hi:[1,0] neg_lo:[0,1] neg_hi:[0,1]
	v_pk_mul_f32 v[80:81], v[80:81], v[160:161] op_sel_hi:[1,0]
	v_pk_mul_f32 v[82:83], v[82:83], v[160:161] op_sel_hi:[1,0]
	s_waitcnt vmcnt(10)
	v_pk_mul_f32 v[80:81], v[96:97], v[80:81]
	v_pk_mul_f32 v[82:83], v[98:99], v[82:83]
	ds_write_b128 v128, v[80:83] offset:32800
	v_pk_add_f32 v[80:81], v[88:89], v[156:157] op_sel_hi:[1,0] neg_lo:[0,1] neg_hi:[0,1]
	v_pk_add_f32 v[82:83], v[90:91], v[156:157] op_sel_hi:[1,0] neg_lo:[0,1] neg_hi:[0,1]
	v_pk_mul_f32 v[80:81], v[80:81], v[160:161] op_sel_hi:[1,0]
	v_pk_mul_f32 v[82:83], v[82:83], v[160:161] op_sel_hi:[1,0]
	s_waitcnt vmcnt(9)
	v_pk_mul_f32 v[80:81], v[80:81], v[100:101]
	v_pk_mul_f32 v[82:83], v[82:83], v[102:103]
	ds_write_b128 v128, v[80:83] offset:32832
	v_pk_add_f32 v[80:81], v[92:93], v[156:157] op_sel_hi:[1,0] neg_lo:[0,1] neg_hi:[0,1]
	v_pk_add_f32 v[82:83], v[94:95], v[156:157] op_sel_hi:[1,0] neg_lo:[0,1] neg_hi:[0,1]
	v_pk_mul_f32 v[80:81], v[80:81], v[160:161] op_sel_hi:[1,0]
	v_pk_mul_f32 v[82:83], v[82:83], v[160:161] op_sel_hi:[1,0]
	s_waitcnt vmcnt(8)
	v_pk_mul_f32 v[80:81], v[80:81], v[108:109]
	v_pk_mul_f32 v[82:83], v[82:83], v[110:111]
	ds_write_b128 v128, v[80:83] offset:32864
	s_waitcnt vmcnt(7)
	v_pk_mul_f32 v[64:65], v[64:65], v[112:113]
	v_pk_mul_f32 v[66:67], v[66:67], v[114:115]
	ds_write_b128 v128, v[64:67] offset:32896
	v_pk_add_f32 v[64:65], v[68:69], v[156:157] op_sel_hi:[1,0] neg_lo:[0,1] neg_hi:[0,1]
	v_pk_add_f32 v[66:67], v[70:71], v[156:157] op_sel_hi:[1,0] neg_lo:[0,1] neg_hi:[0,1]
	v_pk_mul_f32 v[64:65], v[64:65], v[160:161] op_sel_hi:[1,0]
	v_pk_mul_f32 v[66:67], v[66:67], v[160:161] op_sel_hi:[1,0]
	s_waitcnt vmcnt(6)
	v_pk_mul_f32 v[64:65], v[64:65], v[116:117]
	v_pk_mul_f32 v[66:67], v[66:67], v[118:119]
	ds_write_b128 v128, v[64:67] offset:32928
	v_pk_add_f32 v[64:65], v[72:73], v[156:157] op_sel_hi:[1,0] neg_lo:[0,1] neg_hi:[0,1]
	v_pk_add_f32 v[66:67], v[74:75], v[156:157] op_sel_hi:[1,0] neg_lo:[0,1] neg_hi:[0,1]
	v_pk_mul_f32 v[64:65], v[64:65], v[160:161] op_sel_hi:[1,0]
	v_pk_mul_f32 v[66:67], v[66:67], v[160:161] op_sel_hi:[1,0]
	s_waitcnt vmcnt(5)
	v_pk_mul_f32 v[64:65], v[64:65], v[120:121]
	v_pk_mul_f32 v[66:67], v[66:67], v[122:123]
	ds_write_b128 v128, v[64:67] offset:32960
	v_pk_add_f32 v[64:65], v[76:77], v[156:157] op_sel_hi:[1,0] neg_lo:[0,1] neg_hi:[0,1]
	v_pk_add_f32 v[66:67], v[78:79], v[156:157] op_sel_hi:[1,0] neg_lo:[0,1] neg_hi:[0,1]
	v_pk_mul_f32 v[64:65], v[64:65], v[160:161] op_sel_hi:[1,0]
	v_pk_mul_f32 v[66:67], v[66:67], v[160:161] op_sel_hi:[1,0]
	s_waitcnt vmcnt(4)
	v_pk_mul_f32 v[64:65], v[64:65], v[124:125]
	v_pk_mul_f32 v[66:67], v[66:67], v[126:127]
	ds_write_b128 v128, v[64:67] offset:32992
	s_waitcnt lgkmcnt(0)
	ds_read_b128 v[64:67], v138 offset:32768
	ds_read_b128 v[68:71], v138 offset:32784
	s_waitcnt vmcnt(3)
	v_lshlrev_b32_e32 v74, 16, v140
	v_and_b32_e32 v75, 0xffff0000, v140
	v_lshlrev_b32_e32 v76, 16, v141
	v_and_b32_e32 v77, 0xffff0000, v141
	v_lshlrev_b32_e32 v78, 16, v142
	v_and_b32_e32 v79, 0xffff0000, v142
	v_lshlrev_b32_e32 v80, 16, v143
	v_and_b32_e32 v81, 0xffff0000, v143
	s_waitcnt lgkmcnt(1)
	v_pk_mul_f32 v[66:67], v[66:67], v[76:77]
	v_pk_mul_f32 v[64:65], v[64:65], v[74:75]
	s_waitcnt lgkmcnt(0)
	v_pk_mul_f32 v[70:71], v[70:71], v[80:81]
	v_pk_mul_f32 v[68:69], v[68:69], v[78:79]
	v_lshl_add_u64 v[72:73], s[24:25], 0, v[158:159]
	v_cvt_pk_bf16_f32 v64, v64, v65
	v_cvt_pk_bf16_f32 v65, v66, v67
	v_cvt_pk_bf16_f32 v66, v68, v69
	v_cvt_pk_bf16_f32 v67, v70, v71
	global_store_dwordx4 v[72:73], v[64:67], off sc1
	ds_read_b128 v[64:67], v138 offset:34944
	ds_read_b128 v[68:71], v138 offset:34960
	s_waitcnt vmcnt(3)
	v_lshlrev_b32_e32 v74, 16, v144
	v_and_b32_e32 v75, 0xffff0000, v144
	v_lshlrev_b32_e32 v76, 16, v145
	v_and_b32_e32 v77, 0xffff0000, v145
	v_lshlrev_b32_e32 v78, 16, v146
	v_and_b32_e32 v79, 0xffff0000, v146
	v_lshlrev_b32_e32 v80, 16, v147
	v_and_b32_e32 v81, 0xffff0000, v147
	s_waitcnt lgkmcnt(1)
	v_pk_mul_f32 v[66:67], v[66:67], v[76:77]
	v_pk_mul_f32 v[64:65], v[64:65], v[74:75]
	s_waitcnt lgkmcnt(0)
	v_pk_mul_f32 v[68:69], v[68:69], v[78:79]
	v_pk_mul_f32 v[70:71], v[70:71], v[80:81]
	v_cvt_pk_bf16_f32 v64, v64, v65
	v_cvt_pk_bf16_f32 v65, v66, v67
	v_cvt_pk_bf16_f32 v66, v68, v69
	v_add_co_u32_e32 v68, vcc, s73, v72
	v_cvt_pk_bf16_f32 v67, v70, v71
	s_nop 0
	v_addc_co_u32_e32 v69, vcc, 0, v73, vcc
	global_store_dwordx4 v[68:69], v[64:67], off sc1
	ds_read_b128 v[64:67], v138 offset:37120
	ds_read_b128 v[68:71], v138 offset:37136
	s_waitcnt vmcnt(3)
	v_lshlrev_b32_e32 v74, 16, v148
	v_and_b32_e32 v75, 0xffff0000, v148
	v_lshlrev_b32_e32 v76, 16, v149
	v_and_b32_e32 v77, 0xffff0000, v149
	v_lshlrev_b32_e32 v78, 16, v150
	v_and_b32_e32 v79, 0xffff0000, v150
	v_lshlrev_b32_e32 v80, 16, v151
	v_and_b32_e32 v81, 0xffff0000, v151
	s_waitcnt lgkmcnt(1)
	v_pk_mul_f32 v[66:67], v[66:67], v[76:77]
	v_pk_mul_f32 v[64:65], v[64:65], v[74:75]
	s_waitcnt lgkmcnt(0)
	v_pk_mul_f32 v[68:69], v[68:69], v[78:79]
	v_pk_mul_f32 v[70:71], v[70:71], v[80:81]
	v_cvt_pk_bf16_f32 v64, v64, v65
	v_cvt_pk_bf16_f32 v65, v66, v67
	v_cvt_pk_bf16_f32 v66, v68, v69
	v_add_co_u32_e32 v68, vcc, s78, v72
	v_cvt_pk_bf16_f32 v67, v70, v71
	s_nop 0
	v_addc_co_u32_e32 v69, vcc, 0, v73, vcc
	global_store_dwordx4 v[68:69], v[64:67], off sc1
	ds_read_b128 v[64:67], v138 offset:39296
	ds_read_b128 v[68:71], v138 offset:39312
	s_waitcnt vmcnt(3)
	v_lshlrev_b32_e32 v74, 16, v152
	v_and_b32_e32 v75, 0xffff0000, v152
	v_lshlrev_b32_e32 v76, 16, v153
	v_and_b32_e32 v77, 0xffff0000, v153
	v_lshlrev_b32_e32 v78, 16, v154
	v_and_b32_e32 v79, 0xffff0000, v154
	v_lshlrev_b32_e32 v80, 16, v155
	v_and_b32_e32 v81, 0xffff0000, v155
	s_waitcnt lgkmcnt(1)
	v_pk_mul_f32 v[66:67], v[66:67], v[76:77]
	v_pk_mul_f32 v[64:65], v[64:65], v[74:75]
	s_waitcnt lgkmcnt(0)
	v_pk_mul_f32 v[68:69], v[68:69], v[78:79]
	v_pk_mul_f32 v[70:71], v[70:71], v[80:81]
	v_cvt_pk_bf16_f32 v64, v64, v65
	v_cvt_pk_bf16_f32 v65, v66, v67
	v_cvt_pk_bf16_f32 v66, v68, v69
	v_add_co_u32_e32 v68, vcc, s79, v72
	v_cvt_pk_bf16_f32 v67, v70, v71
	s_nop 0
	v_addc_co_u32_e32 v69, vcc, 0, v73, vcc
	global_store_dwordx4 v[68:69], v[64:67], off sc1
	s_waitcnt lgkmcnt(0)
	ds_read_b128 v[64:67], v139 offset:24576
	ds_read_b128 v[68:71], v139 offset:24592
	global_load_dwordx4 v[72:75], v[130:131], off
	ds_read_b128 v[76:79], v139 offset:24608
	ds_read_b128 v[80:83], v139 offset:24624
	s_waitcnt lgkmcnt(3)
	v_pk_add_f32 v[64:65], v[64:65], 0 op_sel_hi:[1,0]
	s_nop 0
	v_pk_add_f32 v[64:65], v[64:65], v[66:67]
	s_waitcnt lgkmcnt(2)
	v_pk_add_f32 v[64:65], v[64:65], v[68:69]
	s_nop 0
	v_pk_add_f32 v[64:65], v[64:65], v[70:71]
	s_waitcnt lgkmcnt(1)
	v_pk_add_f32 v[68:69], v[64:65], v[76:77]
	global_load_dwordx4 v[64:67], v[130:131], off offset:32
	v_pk_add_f32 v[68:69], v[68:69], v[78:79]
	s_waitcnt lgkmcnt(0)
	v_pk_add_f32 v[68:69], v[68:69], v[80:81]
	s_nop 0
	v_pk_add_f32 v[68:69], v[68:69], v[82:83]
	s_nop 0
	v_pk_mul_f32 v[112:113], v[68:69], s[26:27] op_sel_hi:[1,0]
	s_nop 0
	v_fma_f32 v68, -v112, v112, v113
	v_max_f32_e32 v76, 0, v68
	v_add_f32_e32 v76, 0x358637bd, v76
	v_mul_f32_e32 v77, 0x4f800000, v76
	v_cmp_gt_f32_e32 vcc, s67, v76
	global_load_dwordx4 v[68:71], v[130:131], off offset:64
	v_pk_add_f32 v[48:49], v[48:49], v[112:113] op_sel_hi:[1,0] neg_lo:[0,1] neg_hi:[0,1]
	v_cndmask_b32_e32 v88, v76, v77, vcc
	v_sqrt_f32_e32 v84, v88
	global_load_dwordx4 v[76:79], v[130:131], off offset:96
	v_pk_add_f32 v[50:51], v[50:51], v[112:113] op_sel_hi:[1,0] neg_lo:[0,1] neg_hi:[0,1]
	v_pk_add_f32 v[32:33], v[32:33], v[112:113] op_sel_hi:[1,0] neg_lo:[0,1] neg_hi:[0,1]
	v_add_u32_e32 v80, -1, v84
	v_fma_f32 v81, -v80, v84, v88
	v_cmp_ge_f32_e64 s[0:1], 0, v81
	v_add_u32_e32 v86, 1, v84
	v_pk_add_f32 v[34:35], v[34:35], v[112:113] op_sel_hi:[1,0] neg_lo:[0,1] neg_hi:[0,1]
	v_cndmask_b32_e64 v85, v84, v80, s[0:1]
	v_fma_f32 v84, -v86, v84, v88
	v_cmp_lt_f32_e64 s[0:1], 0, v84
	global_load_dwordx4 v[80:83], v[130:131], off offset:128
	s_nop 0
	v_cndmask_b32_e64 v84, v85, v86, s[0:1]
	v_mul_f32_e32 v85, 0x37800000, v84
	v_cndmask_b32_e32 v89, v84, v85, vcc
	v_cmp_class_f32_e32 vcc, v88, v136
	global_load_dwordx4 v[84:87], v[130:131], off offset:160
	s_nop 0
	v_cndmask_b32_e32 v116, v89, v88, vcc
	v_add_u32_e32 v88, 64, v132
	v_ashrrev_i32_e32 v89, 31, v88
	v_lshlrev_b64 v[88:89], 12, v[88:89]
	v_lshl_add_u64 v[88:89], v[88:89], 0, v[134:135]
	v_lshlrev_b64 v[114:115], 1, v[88:89]
	global_load_dwordx4 v[88:91], v[130:131], off offset:192
	v_lshl_add_u64 v[104:105], s[22:23], 0, v[114:115]
	v_add_co_u32_e32 v100, vcc, s73, v104
	v_div_scale_f32 v117, s[0:1], v116, v116, 1.0
	s_nop 0
	v_addc_co_u32_e32 v101, vcc, 0, v105, vcc
	global_load_dwordx4 v[92:95], v[130:131], off offset:224
	global_load_dwordx4 v[96:99], v[104:105], off nt
	s_nop 0
	global_load_dwordx4 v[100:103], v[100:101], off nt
	v_add_co_u32_e32 v106, vcc, s78, v104
	v_rcp_f32_e32 v118, v117
	s_nop 0
	v_addc_co_u32_e32 v107, vcc, 0, v105, vcc
	v_add_co_u32_e32 v108, vcc, 0x30000, v104
	v_fma_f32 v119, -v117, v118, 1.0
	s_nop 0
	v_addc_co_u32_e32 v109, vcc, 0, v105, vcc
	global_load_dwordx4 v[104:107], v[106:107], off nt
	s_nop 0
	global_load_dwordx4 v[108:111], v[108:109], off nt
	v_fmac_f32_e32 v118, v119, v118
	v_div_scale_f32 v119, vcc, 1.0, v116, 1.0
	v_mul_f32_e32 v120, v119, v118
	v_fma_f32 v121, -v117, v120, v119
	v_fmac_f32_e32 v120, v121, v118
	v_fma_f32 v117, -v117, v120, v119
	v_div_fmas_f32 v117, v117, v118, v120
	v_div_fixup_f32 v116, v117, v116, 1.0
	v_pk_mul_f32 v[48:49], v[48:49], v[116:117] op_sel_hi:[1,0]
	v_pk_mul_f32 v[50:51], v[50:51], v[116:117] op_sel_hi:[1,0]
	v_pk_mul_f32 v[32:33], v[32:33], v[116:117] op_sel_hi:[1,0]
	v_pk_mul_f32 v[34:35], v[34:35], v[116:117] op_sel_hi:[1,0]
	s_waitcnt vmcnt(11)
	v_pk_mul_f32 v[48:49], v[72:73], v[48:49]
	v_pk_mul_f32 v[50:51], v[74:75], v[50:51]
	ds_write_b128 v128, v[48:51] offset:32768
	v_pk_add_f32 v[48:49], v[52:53], v[112:113] op_sel_hi:[1,0] neg_lo:[0,1] neg_hi:[0,1]
	v_pk_add_f32 v[50:51], v[54:55], v[112:113] op_sel_hi:[1,0] neg_lo:[0,1] neg_hi:[0,1]
	v_pk_mul_f32 v[48:49], v[48:49], v[116:117] op_sel_hi:[1,0]
	v_pk_mul_f32 v[50:51], v[50:51], v[116:117] op_sel_hi:[1,0]
	s_waitcnt vmcnt(10)
	v_pk_mul_f32 v[48:49], v[64:65], v[48:49]
	v_pk_mul_f32 v[50:51], v[66:67], v[50:51]
	ds_write_b128 v128, v[48:51] offset:32800
	v_pk_add_f32 v[48:49], v[56:57], v[112:113] op_sel_hi:[1,0] neg_lo:[0,1] neg_hi:[0,1]
	v_pk_add_f32 v[50:51], v[58:59], v[112:113] op_sel_hi:[1,0] neg_lo:[0,1] neg_hi:[0,1]
	v_pk_mul_f32 v[48:49], v[48:49], v[116:117] op_sel_hi:[1,0]
	v_pk_mul_f32 v[50:51], v[50:51], v[116:117] op_sel_hi:[1,0]
	s_waitcnt vmcnt(9)
	v_pk_mul_f32 v[48:49], v[48:49], v[68:69]
	v_pk_mul_f32 v[50:51], v[50:51], v[70:71]
	ds_write_b128 v128, v[48:51] offset:32832
	v_pk_add_f32 v[48:49], v[60:61], v[112:113] op_sel_hi:[1,0] neg_lo:[0,1] neg_hi:[0,1]
	v_pk_add_f32 v[50:51], v[62:63], v[112:113] op_sel_hi:[1,0] neg_lo:[0,1] neg_hi:[0,1]
	v_pk_mul_f32 v[48:49], v[48:49], v[116:117] op_sel_hi:[1,0]
	v_pk_mul_f32 v[50:51], v[50:51], v[116:117] op_sel_hi:[1,0]
	s_waitcnt vmcnt(8)
	v_pk_mul_f32 v[48:49], v[48:49], v[76:77]
	v_pk_mul_f32 v[50:51], v[50:51], v[78:79]
	ds_write_b128 v128, v[48:51] offset:32864
	s_waitcnt vmcnt(7)
	v_pk_mul_f32 v[32:33], v[32:33], v[80:81]
	v_pk_mul_f32 v[34:35], v[34:35], v[82:83]
	ds_write_b128 v128, v[32:35] offset:32896
	v_pk_add_f32 v[32:33], v[36:37], v[112:113] op_sel_hi:[1,0] neg_lo:[0,1] neg_hi:[0,1]
	v_pk_add_f32 v[34:35], v[38:39], v[112:113] op_sel_hi:[1,0] neg_lo:[0,1] neg_hi:[0,1]
	v_pk_mul_f32 v[32:33], v[32:33], v[116:117] op_sel_hi:[1,0]
	v_pk_mul_f32 v[34:35], v[34:35], v[116:117] op_sel_hi:[1,0]
	s_waitcnt vmcnt(6)
	v_pk_mul_f32 v[32:33], v[32:33], v[84:85]
	v_pk_mul_f32 v[34:35], v[34:35], v[86:87]
	ds_write_b128 v128, v[32:35] offset:32928
	v_pk_add_f32 v[32:33], v[40:41], v[112:113] op_sel_hi:[1,0] neg_lo:[0,1] neg_hi:[0,1]
	v_pk_add_f32 v[34:35], v[42:43], v[112:113] op_sel_hi:[1,0] neg_lo:[0,1] neg_hi:[0,1]
	v_pk_mul_f32 v[32:33], v[32:33], v[116:117] op_sel_hi:[1,0]
	v_pk_mul_f32 v[34:35], v[34:35], v[116:117] op_sel_hi:[1,0]
	s_waitcnt vmcnt(5)
	v_pk_mul_f32 v[32:33], v[32:33], v[88:89]
	v_pk_mul_f32 v[34:35], v[34:35], v[90:91]
	ds_write_b128 v128, v[32:35] offset:32960
	v_pk_add_f32 v[32:33], v[44:45], v[112:113] op_sel_hi:[1,0] neg_lo:[0,1] neg_hi:[0,1]
	v_pk_add_f32 v[34:35], v[46:47], v[112:113] op_sel_hi:[1,0] neg_lo:[0,1] neg_hi:[0,1]
	v_pk_mul_f32 v[32:33], v[32:33], v[116:117] op_sel_hi:[1,0]
	v_pk_mul_f32 v[34:35], v[34:35], v[116:117] op_sel_hi:[1,0]
	s_waitcnt vmcnt(4)
	v_pk_mul_f32 v[32:33], v[32:33], v[92:93]
	v_pk_mul_f32 v[34:35], v[34:35], v[94:95]
	ds_write_b128 v128, v[32:35] offset:32992
	s_waitcnt lgkmcnt(0)
	ds_read_b128 v[32:35], v138 offset:32768
	ds_read_b128 v[36:39], v138 offset:32784
	s_waitcnt vmcnt(3)
	v_lshlrev_b32_e32 v42, 16, v96
	v_and_b32_e32 v43, 0xffff0000, v96
	v_lshlrev_b32_e32 v44, 16, v97
	v_and_b32_e32 v45, 0xffff0000, v97
	v_lshlrev_b32_e32 v46, 16, v98
	v_and_b32_e32 v47, 0xffff0000, v98
	v_lshlrev_b32_e32 v48, 16, v99
	v_and_b32_e32 v49, 0xffff0000, v99
	s_waitcnt lgkmcnt(1)
	v_pk_mul_f32 v[34:35], v[34:35], v[44:45]
	v_pk_mul_f32 v[32:33], v[32:33], v[42:43]
	s_waitcnt lgkmcnt(0)
	v_pk_mul_f32 v[38:39], v[38:39], v[48:49]
	v_pk_mul_f32 v[36:37], v[36:37], v[46:47]
	v_lshl_add_u64 v[40:41], s[24:25], 0, v[114:115]
	v_cvt_pk_bf16_f32 v32, v32, v33
	v_cvt_pk_bf16_f32 v33, v34, v35
	v_cvt_pk_bf16_f32 v34, v36, v37
	v_cvt_pk_bf16_f32 v35, v38, v39
	global_store_dwordx4 v[40:41], v[32:35], off sc1
	ds_read_b128 v[32:35], v138 offset:34944
	ds_read_b128 v[36:39], v138 offset:34960
	s_waitcnt vmcnt(3)
	v_lshlrev_b32_e32 v42, 16, v100
	v_and_b32_e32 v43, 0xffff0000, v100
	v_lshlrev_b32_e32 v44, 16, v101
	v_and_b32_e32 v45, 0xffff0000, v101
	v_lshlrev_b32_e32 v46, 16, v102
	v_and_b32_e32 v47, 0xffff0000, v102
	v_lshlrev_b32_e32 v48, 16, v103
	v_and_b32_e32 v49, 0xffff0000, v103
	s_waitcnt lgkmcnt(1)
	v_pk_mul_f32 v[34:35], v[34:35], v[44:45]
	v_pk_mul_f32 v[32:33], v[32:33], v[42:43]
	s_waitcnt lgkmcnt(0)
	v_pk_mul_f32 v[36:37], v[36:37], v[46:47]
	v_pk_mul_f32 v[38:39], v[38:39], v[48:49]
	v_cvt_pk_bf16_f32 v32, v32, v33
	v_cvt_pk_bf16_f32 v33, v34, v35
	v_cvt_pk_bf16_f32 v34, v36, v37
	v_add_co_u32_e32 v36, vcc, s73, v40
	v_cvt_pk_bf16_f32 v35, v38, v39
	s_nop 0
	v_addc_co_u32_e32 v37, vcc, 0, v41, vcc
	global_store_dwordx4 v[36:37], v[32:35], off sc1
	ds_read_b128 v[32:35], v138 offset:37120
	ds_read_b128 v[36:39], v138 offset:37136
	s_waitcnt vmcnt(3)
	v_lshlrev_b32_e32 v42, 16, v104
	v_and_b32_e32 v43, 0xffff0000, v104
	v_lshlrev_b32_e32 v44, 16, v105
	v_and_b32_e32 v45, 0xffff0000, v105
	v_lshlrev_b32_e32 v46, 16, v106
	v_and_b32_e32 v47, 0xffff0000, v106
	v_lshlrev_b32_e32 v48, 16, v107
	v_and_b32_e32 v49, 0xffff0000, v107
	s_waitcnt lgkmcnt(1)
	v_pk_mul_f32 v[34:35], v[34:35], v[44:45]
	v_pk_mul_f32 v[32:33], v[32:33], v[42:43]
	s_waitcnt lgkmcnt(0)
	v_pk_mul_f32 v[36:37], v[36:37], v[46:47]
	v_pk_mul_f32 v[38:39], v[38:39], v[48:49]
	v_cvt_pk_bf16_f32 v32, v32, v33
	v_cvt_pk_bf16_f32 v33, v34, v35
	v_cvt_pk_bf16_f32 v34, v36, v37
	v_add_co_u32_e32 v36, vcc, s78, v40
	v_cvt_pk_bf16_f32 v35, v38, v39
	s_nop 0
	v_addc_co_u32_e32 v37, vcc, 0, v41, vcc
	global_store_dwordx4 v[36:37], v[32:35], off sc1
	ds_read_b128 v[32:35], v138 offset:39296
	ds_read_b128 v[36:39], v138 offset:39312
	s_waitcnt vmcnt(3)
	v_lshlrev_b32_e32 v42, 16, v108
	v_and_b32_e32 v43, 0xffff0000, v108
	v_lshlrev_b32_e32 v44, 16, v109
	v_and_b32_e32 v45, 0xffff0000, v109
	v_lshlrev_b32_e32 v46, 16, v110
	v_and_b32_e32 v47, 0xffff0000, v110
	v_lshlrev_b32_e32 v48, 16, v111
	v_and_b32_e32 v49, 0xffff0000, v111
	s_waitcnt lgkmcnt(1)
	v_pk_mul_f32 v[34:35], v[34:35], v[44:45]
	v_pk_mul_f32 v[32:33], v[32:33], v[42:43]
	s_waitcnt lgkmcnt(0)
	v_pk_mul_f32 v[36:37], v[36:37], v[46:47]
	v_pk_mul_f32 v[38:39], v[38:39], v[48:49]
	v_cvt_pk_bf16_f32 v32, v32, v33
	v_cvt_pk_bf16_f32 v33, v34, v35
	v_cvt_pk_bf16_f32 v34, v36, v37
	v_add_co_u32_e32 v36, vcc, s79, v40
	v_cvt_pk_bf16_f32 v35, v38, v39
	s_nop 0
	v_addc_co_u32_e32 v37, vcc, 0, v41, vcc
	global_store_dwordx4 v[36:37], v[32:35], off sc1
	s_waitcnt lgkmcnt(0)
	ds_read_b128 v[32:35], v139 offset:26624
	ds_read_b128 v[36:39], v139 offset:26640
	global_load_dwordx4 v[40:43], v[130:131], off
	ds_read_b128 v[44:47], v139 offset:26656
	ds_read_b128 v[48:51], v139 offset:26672
	s_waitcnt lgkmcnt(3)
	v_pk_add_f32 v[32:33], v[32:33], 0 op_sel_hi:[1,0]
	s_nop 0
	v_pk_add_f32 v[32:33], v[32:33], v[34:35]
	s_waitcnt lgkmcnt(2)
	v_pk_add_f32 v[32:33], v[32:33], v[36:37]
	s_nop 0
	v_pk_add_f32 v[32:33], v[32:33], v[38:39]
	s_waitcnt lgkmcnt(1)
	v_pk_add_f32 v[36:37], v[32:33], v[44:45]
	global_load_dwordx4 v[32:35], v[130:131], off offset:32
	v_pk_add_f32 v[36:37], v[36:37], v[46:47]
	s_waitcnt lgkmcnt(0)
	v_pk_add_f32 v[36:37], v[36:37], v[48:49]
	s_nop 0
	v_pk_add_f32 v[36:37], v[36:37], v[50:51]
	s_nop 0
	v_pk_mul_f32 v[80:81], v[36:37], s[26:27] op_sel_hi:[1,0]
	s_nop 0
	v_fma_f32 v36, -v80, v80, v81
	v_max_f32_e32 v44, 0, v36
	v_add_f32_e32 v44, 0x358637bd, v44
	v_mul_f32_e32 v45, 0x4f800000, v44
	v_cmp_gt_f32_e32 vcc, s67, v44
	global_load_dwordx4 v[36:39], v[130:131], off offset:64
	v_pk_add_f32 v[16:17], v[16:17], v[80:81] op_sel_hi:[1,0] neg_lo:[0,1] neg_hi:[0,1]
	v_cndmask_b32_e32 v56, v44, v45, vcc
	v_sqrt_f32_e32 v52, v56
	global_load_dwordx4 v[44:47], v[130:131], off offset:96
	v_pk_add_f32 v[18:19], v[18:19], v[80:81] op_sel_hi:[1,0] neg_lo:[0,1] neg_hi:[0,1]
	v_pk_add_f32 v[0:1], v[0:1], v[80:81] op_sel_hi:[1,0] neg_lo:[0,1] neg_hi:[0,1]
	v_add_u32_e32 v48, -1, v52
	v_fma_f32 v49, -v48, v52, v56
	v_cmp_ge_f32_e64 s[0:1], 0, v49
	v_add_u32_e32 v54, 1, v52
	v_pk_add_f32 v[2:3], v[2:3], v[80:81] op_sel_hi:[1,0] neg_lo:[0,1] neg_hi:[0,1]
	v_cndmask_b32_e64 v53, v52, v48, s[0:1]
	v_fma_f32 v52, -v54, v52, v56
	v_cmp_lt_f32_e64 s[0:1], 0, v52
	global_load_dwordx4 v[48:51], v[130:131], off offset:128
	s_nop 0
	v_cndmask_b32_e64 v52, v53, v54, s[0:1]
	v_mul_f32_e32 v53, 0x37800000, v52
	v_cndmask_b32_e32 v57, v52, v53, vcc
	v_cmp_class_f32_e32 vcc, v56, v136
	global_load_dwordx4 v[52:55], v[130:131], off offset:160
	s_nop 0
	v_cndmask_b32_e32 v84, v57, v56, vcc
	v_add_u32_e32 v56, 0x60, v132
	v_ashrrev_i32_e32 v57, 31, v56
	v_lshlrev_b64 v[56:57], 12, v[56:57]
	v_lshl_add_u64 v[56:57], v[56:57], 0, v[134:135]
	v_lshlrev_b64 v[82:83], 1, v[56:57]
	global_load_dwordx4 v[56:59], v[130:131], off offset:192
	v_lshl_add_u64 v[72:73], s[22:23], 0, v[82:83]
	v_add_co_u32_e32 v68, vcc, s73, v72
	v_div_scale_f32 v85, s[0:1], v84, v84, 1.0
	s_nop 0
	v_addc_co_u32_e32 v69, vcc, 0, v73, vcc
	global_load_dwordx4 v[60:63], v[130:131], off offset:224
	global_load_dwordx4 v[64:67], v[72:73], off nt
	s_nop 0
	global_load_dwordx4 v[68:71], v[68:69], off nt
	v_add_co_u32_e32 v74, vcc, s78, v72
	v_rcp_f32_e32 v86, v85
	s_nop 0
	v_addc_co_u32_e32 v75, vcc, 0, v73, vcc
	v_add_co_u32_e32 v76, vcc, 0x30000, v72
	v_fma_f32 v87, -v85, v86, 1.0
	s_nop 0
	v_addc_co_u32_e32 v77, vcc, 0, v73, vcc
	global_load_dwordx4 v[72:75], v[74:75], off nt
	s_nop 0
	global_load_dwordx4 v[76:79], v[76:77], off nt
	v_fmac_f32_e32 v86, v87, v86
	v_div_scale_f32 v87, vcc, 1.0, v84, 1.0
	v_mul_f32_e32 v88, v87, v86
	v_fma_f32 v89, -v85, v88, v87
	v_fmac_f32_e32 v88, v89, v86
	v_fma_f32 v85, -v85, v88, v87
	v_div_fmas_f32 v85, v85, v86, v88
	v_div_fixup_f32 v84, v85, v84, 1.0
	v_pk_mul_f32 v[16:17], v[16:17], v[84:85] op_sel_hi:[1,0]
	v_pk_mul_f32 v[18:19], v[18:19], v[84:85] op_sel_hi:[1,0]
	v_pk_mul_f32 v[0:1], v[0:1], v[84:85] op_sel_hi:[1,0]
	v_pk_mul_f32 v[2:3], v[2:3], v[84:85] op_sel_hi:[1,0]
	s_waitcnt vmcnt(11)
	v_pk_mul_f32 v[16:17], v[40:41], v[16:17]
	v_pk_mul_f32 v[18:19], v[42:43], v[18:19]
	ds_write_b128 v128, v[16:19] offset:32768
	v_pk_add_f32 v[16:17], v[20:21], v[80:81] op_sel_hi:[1,0] neg_lo:[0,1] neg_hi:[0,1]
	v_pk_add_f32 v[18:19], v[22:23], v[80:81] op_sel_hi:[1,0] neg_lo:[0,1] neg_hi:[0,1]
	v_pk_mul_f32 v[16:17], v[16:17], v[84:85] op_sel_hi:[1,0]
	v_pk_mul_f32 v[18:19], v[18:19], v[84:85] op_sel_hi:[1,0]
	s_waitcnt vmcnt(10)
	v_pk_mul_f32 v[16:17], v[32:33], v[16:17]
	v_pk_mul_f32 v[18:19], v[34:35], v[18:19]
	ds_write_b128 v128, v[16:19] offset:32800
	v_pk_add_f32 v[16:17], v[24:25], v[80:81] op_sel_hi:[1,0] neg_lo:[0,1] neg_hi:[0,1]
	v_pk_add_f32 v[18:19], v[26:27], v[80:81] op_sel_hi:[1,0] neg_lo:[0,1] neg_hi:[0,1]
	v_pk_mul_f32 v[16:17], v[16:17], v[84:85] op_sel_hi:[1,0]
	v_pk_mul_f32 v[18:19], v[18:19], v[84:85] op_sel_hi:[1,0]
	v_readlane_b32 s0, v254, 6
	s_add_i32 s82, s82, s0
	s_cmpk_gt_i32 s82, 0x3ff
	v_readlane_b32 s1, v254, 7
	s_waitcnt vmcnt(9)
	v_pk_mul_f32 v[16:17], v[16:17], v[36:37]
	v_pk_mul_f32 v[18:19], v[18:19], v[38:39]
	ds_write_b128 v128, v[16:19] offset:32832
	v_pk_add_f32 v[16:17], v[28:29], v[80:81] op_sel_hi:[1,0] neg_lo:[0,1] neg_hi:[0,1]
	v_pk_add_f32 v[18:19], v[30:31], v[80:81] op_sel_hi:[1,0] neg_lo:[0,1] neg_hi:[0,1]
	v_pk_mul_f32 v[16:17], v[16:17], v[84:85] op_sel_hi:[1,0]
	v_pk_mul_f32 v[18:19], v[18:19], v[84:85] op_sel_hi:[1,0]
	s_waitcnt vmcnt(8)
	v_pk_mul_f32 v[16:17], v[16:17], v[44:45]
	v_pk_mul_f32 v[18:19], v[18:19], v[46:47]
	ds_write_b128 v128, v[16:19] offset:32864
	s_waitcnt vmcnt(7)
	v_pk_mul_f32 v[0:1], v[0:1], v[48:49]
	v_pk_mul_f32 v[2:3], v[2:3], v[50:51]
	ds_write_b128 v128, v[0:3] offset:32896
	v_pk_add_f32 v[0:1], v[4:5], v[80:81] op_sel_hi:[1,0] neg_lo:[0,1] neg_hi:[0,1]
	v_pk_add_f32 v[2:3], v[6:7], v[80:81] op_sel_hi:[1,0] neg_lo:[0,1] neg_hi:[0,1]
	v_pk_mul_f32 v[0:1], v[0:1], v[84:85] op_sel_hi:[1,0]
	v_pk_mul_f32 v[2:3], v[2:3], v[84:85] op_sel_hi:[1,0]
	s_waitcnt vmcnt(6)
	v_pk_mul_f32 v[0:1], v[0:1], v[52:53]
	v_pk_mul_f32 v[2:3], v[2:3], v[54:55]
	ds_write_b128 v128, v[0:3] offset:32928
	v_pk_add_f32 v[0:1], v[8:9], v[80:81] op_sel_hi:[1,0] neg_lo:[0,1] neg_hi:[0,1]
	v_pk_add_f32 v[2:3], v[10:11], v[80:81] op_sel_hi:[1,0] neg_lo:[0,1] neg_hi:[0,1]
	v_pk_mul_f32 v[0:1], v[0:1], v[84:85] op_sel_hi:[1,0]
	v_pk_mul_f32 v[2:3], v[2:3], v[84:85] op_sel_hi:[1,0]
	s_waitcnt vmcnt(5)
	v_pk_mul_f32 v[0:1], v[0:1], v[56:57]
	v_pk_mul_f32 v[2:3], v[2:3], v[58:59]
	ds_write_b128 v128, v[0:3] offset:32960
	v_pk_add_f32 v[0:1], v[12:13], v[80:81] op_sel_hi:[1,0] neg_lo:[0,1] neg_hi:[0,1]
	v_pk_add_f32 v[2:3], v[14:15], v[80:81] op_sel_hi:[1,0] neg_lo:[0,1] neg_hi:[0,1]
	v_pk_mul_f32 v[0:1], v[0:1], v[84:85] op_sel_hi:[1,0]
	v_pk_mul_f32 v[2:3], v[2:3], v[84:85] op_sel_hi:[1,0]
	s_waitcnt vmcnt(4)
	v_pk_mul_f32 v[0:1], v[0:1], v[60:61]
	v_pk_mul_f32 v[2:3], v[2:3], v[62:63]
	ds_write_b128 v128, v[0:3] offset:32992
	s_waitcnt lgkmcnt(0)
	ds_read_b128 v[0:3], v138 offset:32768
	ds_read_b128 v[4:7], v138 offset:32784
	s_waitcnt vmcnt(3)
	v_lshlrev_b32_e32 v10, 16, v64
	v_and_b32_e32 v11, 0xffff0000, v64
	v_lshlrev_b32_e32 v12, 16, v65
	v_and_b32_e32 v13, 0xffff0000, v65
	v_lshlrev_b32_e32 v14, 16, v66
	v_and_b32_e32 v15, 0xffff0000, v66
	v_lshlrev_b32_e32 v16, 16, v67
	v_and_b32_e32 v17, 0xffff0000, v67
	s_waitcnt lgkmcnt(1)
	v_pk_mul_f32 v[2:3], v[2:3], v[12:13]
	v_pk_mul_f32 v[0:1], v[0:1], v[10:11]
	s_waitcnt lgkmcnt(0)
	v_pk_mul_f32 v[6:7], v[6:7], v[16:17]
	v_pk_mul_f32 v[4:5], v[4:5], v[14:15]
	v_lshl_add_u64 v[8:9], s[24:25], 0, v[82:83]
	v_cvt_pk_bf16_f32 v0, v0, v1
	v_cvt_pk_bf16_f32 v1, v2, v3
	v_cvt_pk_bf16_f32 v2, v4, v5
	v_cvt_pk_bf16_f32 v3, v6, v7
	global_store_dwordx4 v[8:9], v[0:3], off sc1
	ds_read_b128 v[0:3], v138 offset:34944
	ds_read_b128 v[4:7], v138 offset:34960
	s_waitcnt vmcnt(3)
	v_lshlrev_b32_e32 v10, 16, v68
	v_and_b32_e32 v11, 0xffff0000, v68
	v_lshlrev_b32_e32 v12, 16, v69
	v_and_b32_e32 v13, 0xffff0000, v69
	v_lshlrev_b32_e32 v14, 16, v70
	v_and_b32_e32 v15, 0xffff0000, v70
	v_lshlrev_b32_e32 v16, 16, v71
	v_and_b32_e32 v17, 0xffff0000, v71
	s_waitcnt lgkmcnt(1)
	v_pk_mul_f32 v[2:3], v[2:3], v[12:13]
	v_pk_mul_f32 v[0:1], v[0:1], v[10:11]
	s_waitcnt lgkmcnt(0)
	v_pk_mul_f32 v[4:5], v[4:5], v[14:15]
	v_pk_mul_f32 v[6:7], v[6:7], v[16:17]
	v_cvt_pk_bf16_f32 v0, v0, v1
	v_cvt_pk_bf16_f32 v1, v2, v3
	v_cvt_pk_bf16_f32 v2, v4, v5
	v_add_co_u32_e32 v4, vcc, s73, v8
	v_cvt_pk_bf16_f32 v3, v6, v7
	s_nop 0
	v_addc_co_u32_e32 v5, vcc, 0, v9, vcc
	global_store_dwordx4 v[4:5], v[0:3], off sc1
	ds_read_b128 v[0:3], v138 offset:37120
	ds_read_b128 v[4:7], v138 offset:37136
	s_waitcnt vmcnt(3)
	v_lshlrev_b32_e32 v10, 16, v72
	v_and_b32_e32 v11, 0xffff0000, v72
	v_lshlrev_b32_e32 v12, 16, v73
	v_and_b32_e32 v13, 0xffff0000, v73
	v_lshlrev_b32_e32 v14, 16, v74
	v_and_b32_e32 v15, 0xffff0000, v74
	v_lshlrev_b32_e32 v16, 16, v75
	v_and_b32_e32 v17, 0xffff0000, v75
	s_waitcnt lgkmcnt(1)
	v_pk_mul_f32 v[2:3], v[2:3], v[12:13]
	v_pk_mul_f32 v[0:1], v[0:1], v[10:11]
	s_waitcnt lgkmcnt(0)
	v_pk_mul_f32 v[4:5], v[4:5], v[14:15]
	v_pk_mul_f32 v[6:7], v[6:7], v[16:17]
	v_cvt_pk_bf16_f32 v0, v0, v1
	v_cvt_pk_bf16_f32 v1, v2, v3
	v_cvt_pk_bf16_f32 v2, v4, v5
	v_add_co_u32_e32 v4, vcc, s78, v8
	v_cvt_pk_bf16_f32 v3, v6, v7
	s_nop 0
	v_addc_co_u32_e32 v5, vcc, 0, v9, vcc
	global_store_dwordx4 v[4:5], v[0:3], off sc1
	ds_read_b128 v[0:3], v138 offset:39296
	ds_read_b128 v[4:7], v138 offset:39312
	s_waitcnt vmcnt(3)
	v_lshlrev_b32_e32 v10, 16, v76
	v_and_b32_e32 v11, 0xffff0000, v76
	v_lshlrev_b32_e32 v12, 16, v77
	v_and_b32_e32 v13, 0xffff0000, v77
	v_lshlrev_b32_e32 v14, 16, v78
	v_and_b32_e32 v15, 0xffff0000, v78
	v_lshlrev_b32_e32 v16, 16, v79
	v_and_b32_e32 v17, 0xffff0000, v79
	s_waitcnt lgkmcnt(1)
	v_pk_mul_f32 v[2:3], v[2:3], v[12:13]
	v_pk_mul_f32 v[0:1], v[0:1], v[10:11]
	s_waitcnt lgkmcnt(0)
	v_pk_mul_f32 v[4:5], v[4:5], v[14:15]
	v_pk_mul_f32 v[6:7], v[6:7], v[16:17]
	v_cvt_pk_bf16_f32 v0, v0, v1
	v_cvt_pk_bf16_f32 v1, v2, v3
	v_cvt_pk_bf16_f32 v2, v4, v5
	v_add_co_u32_e32 v4, vcc, 0x30000, v8
	v_cvt_pk_bf16_f32 v3, v6, v7
	s_nop 0
	v_addc_co_u32_e32 v5, vcc, 0, v9, vcc
	global_store_dwordx4 v[4:5], v[0:3], off sc1
	s_waitcnt lgkmcnt(0)
	s_barrier
	s_cbranch_scc1 .LBB0_613

.LBB0_615:
	s_ashr_i32 s8, s0, 12
	s_ashr_i32 s9, s8, 31
	s_and_b32 s1, s0, 0xfff
	s_lshl_b32 s11, s8, 2
	s_lshl_b32 s13, s8, 4
	s_lshl_b64 s[8:9], s[8:9], 12
	s_or_b32 s8, s8, s1
	s_lshl_b64 s[14:15], s[8:9], 5
	s_and_b32 s10, s0, 15
	s_or_b32 s12, s11, s2
	v_lshl_add_u64 v[14:15], v[0:1], 0, s[14:15]
	s_or_b32 s10, s13, s10
	s_ashr_i32 s13, s12, 31
	global_load_dword v62, v[14:15], off
	s_bfe_u32 s3, s0, 0xa0002
	s_ashr_i32 s11, s10, 31
	s_lshl_b64 s[12:13], s[12:13], 10
	s_bfe_u32 s5, s0, 0x80004
	s_lshl_b64 s[10:11], s[10:11], 8
	s_lshl_b64 s[8:9], s[8:9], 11
	s_or_b32 s12, s12, s3
	s_or_b32 s10, s10, s5
	v_lshl_add_u64 v[38:39], v[6:7], 0, s[8:9]
	s_lshl_b64 s[8:9], s[12:13], 5
	s_lshl_b64 s[14:15], s[10:11], 5
	s_lshl_b64 s[12:13], s[12:13], 11
	s_lshl_b64 s[10:11], s[10:11], 11
	v_lshl_add_u64 v[40:41], v[2:3], 0, s[8:9]
	global_load_dwordx4 v[14:17], v[38:39], off offset:16
	v_lshl_add_u64 v[42:43], v[4:5], 0, s[14:15]
	v_lshl_add_u64 v[44:45], v[8:9], 0, s[12:13]
	v_lshl_add_u64 v[46:47], v[10:11], 0, s[10:11]
	global_load_dword v63, v[40:41], off
	global_load_dword v64, v[42:43], off
	global_load_dwordx4 v[18:21], v[38:39], off
	global_load_dwordx4 v[22:25], v[44:45], off
	global_load_dwordx4 v[26:29], v[44:45], off offset:16
	global_load_dwordx4 v[30:33], v[46:47], off
	global_load_dwordx4 v[34:37], v[46:47], off offset:16
	s_add_i32 s0, s0, s4
	s_cmpk_lt_i32 s0, 0x4000
	s_waitcnt vmcnt(5)
	v_max3_f32 v65, v62, v63, v64
	v_sub_f32_e32 v62, v62, v65
	v_sub_f32_e32 v63, v63, v65
	v_exp_f32_e32 v62, v62
	v_sub_f32_e32 v64, v64, v65
	v_exp_f32_e32 v63, v63
	v_exp_f32_e32 v65, v64
	v_add_f32_e32 v64, 0, v62
	s_waitcnt vmcnt(4)
	v_lshlrev_b32_e32 v42, 16, v18
	v_add_f32_e32 v64, v63, v64
	v_add_f32_e32 v64, v65, v64
	v_div_scale_f32 v66, s[8:9], v64, v64, 1.0
	v_rcp_f32_e32 v68, v66
	v_div_scale_f32 v67, vcc, 1.0, v64, 1.0
	v_and_b32_e32 v43, 0xffff0000, v18
	v_fma_f32 v69, -v66, v68, 1.0
	v_fmac_f32_e32 v68, v69, v68
	v_mul_f32_e32 v69, v67, v68
	v_fma_f32 v70, -v66, v69, v67
	v_fmac_f32_e32 v69, v70, v68
	v_fma_f32 v66, -v66, v69, v67
	v_div_fmas_f32 v66, v66, v68, v69
	v_div_fixup_f32 v66, v66, v64, 1.0
	v_lshlrev_b32_e32 v18, 16, v19
	v_and_b32_e32 v19, 0xffff0000, v19
	v_lshlrev_b32_e32 v44, 16, v20
	v_and_b32_e32 v45, 0xffff0000, v20
	v_lshlrev_b32_e32 v20, 16, v21
	v_and_b32_e32 v21, 0xffff0000, v21
	v_mul_f32_e32 v62, v62, v66
	v_lshlrev_b32_e32 v38, 16, v14
	v_and_b32_e32 v39, 0xffff0000, v14
	v_lshlrev_b32_e32 v14, 16, v15
	v_and_b32_e32 v15, 0xffff0000, v15
	v_lshlrev_b32_e32 v40, 16, v16
	v_and_b32_e32 v41, 0xffff0000, v16
	v_lshlrev_b32_e32 v16, 16, v17
	v_and_b32_e32 v17, 0xffff0000, v17
	s_waitcnt vmcnt(3)
	v_lshlrev_b32_e32 v46, 16, v22
	v_and_b32_e32 v47, 0xffff0000, v22
	v_lshlrev_b32_e32 v22, 16, v23
	v_and_b32_e32 v23, 0xffff0000, v23
	v_lshlrev_b32_e32 v48, 16, v24
	v_and_b32_e32 v49, 0xffff0000, v24
	v_lshlrev_b32_e32 v24, 16, v25
	v_and_b32_e32 v25, 0xffff0000, v25
	v_mul_f32_e32 v64, v63, v66
	v_pk_fma_f32 v[18:19], v[62:63], v[18:19], 0 op_sel_hi:[0,1,0]
	v_pk_fma_f32 v[42:43], v[62:63], v[42:43], 0 op_sel_hi:[0,1,0]
	v_pk_fma_f32 v[20:21], v[62:63], v[20:21], 0 op_sel_hi:[0,1,0]
	v_pk_fma_f32 v[44:45], v[62:63], v[44:45], 0 op_sel_hi:[0,1,0]
	s_waitcnt vmcnt(2)
	v_lshlrev_b32_e32 v50, 16, v26
	v_and_b32_e32 v51, 0xffff0000, v26
	v_lshlrev_b32_e32 v26, 16, v27
	v_and_b32_e32 v27, 0xffff0000, v27
	v_lshlrev_b32_e32 v52, 16, v28
	v_and_b32_e32 v53, 0xffff0000, v28
	v_lshlrev_b32_e32 v28, 16, v29
	v_and_b32_e32 v29, 0xffff0000, v29
	s_waitcnt vmcnt(1)
	v_lshlrev_b32_e32 v54, 16, v30
	v_and_b32_e32 v55, 0xffff0000, v30
	v_lshlrev_b32_e32 v30, 16, v31
	v_and_b32_e32 v31, 0xffff0000, v31
	v_lshlrev_b32_e32 v56, 16, v32
	v_and_b32_e32 v57, 0xffff0000, v32
	v_lshlrev_b32_e32 v32, 16, v33
	v_and_b32_e32 v33, 0xffff0000, v33
	v_mul_f32_e32 v66, v65, v66
	v_pk_fma_f32 v[14:15], v[62:63], v[14:15], 0 op_sel_hi:[0,1,0]
	v_pk_fma_f32 v[38:39], v[62:63], v[38:39], 0 op_sel_hi:[0,1,0]
	v_pk_fma_f32 v[16:17], v[62:63], v[16:17], 0 op_sel_hi:[0,1,0]
	v_pk_fma_f32 v[40:41], v[62:63], v[40:41], 0 op_sel_hi:[0,1,0]
	v_pk_fma_f32 v[42:43], v[64:65], v[46:47], v[42:43] op_sel_hi:[0,1,1]
	v_pk_fma_f32 v[18:19], v[64:65], v[22:23], v[18:19] op_sel_hi:[0,1,1]
	v_pk_fma_f32 v[22:23], v[64:65], v[48:49], v[44:45] op_sel_hi:[0,1,1]
	v_pk_fma_f32 v[20:21], v[64:65], v[24:25], v[20:21] op_sel_hi:[0,1,1]
	s_waitcnt vmcnt(0)
	v_lshlrev_b32_e32 v58, 16, v34
	v_and_b32_e32 v59, 0xffff0000, v34
	v_lshlrev_b32_e32 v34, 16, v35
	v_and_b32_e32 v35, 0xffff0000, v35
	v_lshlrev_b32_e32 v60, 16, v36
	v_and_b32_e32 v61, 0xffff0000, v36
	v_lshlrev_b32_e32 v36, 16, v37
	v_and_b32_e32 v37, 0xffff0000, v37
	v_pk_fma_f32 v[24:25], v[64:65], v[50:51], v[38:39] op_sel_hi:[0,1,1]
	v_pk_fma_f32 v[14:15], v[64:65], v[26:27], v[14:15] op_sel_hi:[0,1,1]
	v_pk_fma_f32 v[26:27], v[64:65], v[52:53], v[40:41] op_sel_hi:[0,1,1]
	v_pk_fma_f32 v[16:17], v[64:65], v[28:29], v[16:17] op_sel_hi:[0,1,1]
	v_pk_fma_f32 v[18:19], v[66:67], v[30:31], v[18:19] op_sel_hi:[0,1,1]
	v_pk_fma_f32 v[28:29], v[66:67], v[54:55], v[42:43] op_sel_hi:[0,1,1]
	v_pk_fma_f32 v[20:21], v[66:67], v[32:33], v[20:21] op_sel_hi:[0,1,1]
	v_pk_fma_f32 v[22:23], v[66:67], v[56:57], v[22:23] op_sel_hi:[0,1,1]
	v_pk_fma_f32 v[30:31], v[66:67], v[34:35], v[14:15] op_sel_hi:[0,1,1]
	v_pk_fma_f32 v[24:25], v[66:67], v[58:59], v[24:25] op_sel_hi:[0,1,1]
	v_pk_fma_f32 v[32:33], v[66:67], v[36:37], v[16:17] op_sel_hi:[0,1,1]
	v_pk_fma_f32 v[26:27], v[66:67], v[60:61], v[26:27] op_sel_hi:[0,1,1]
	v_cvt_pk_bf16_f32 v14, v28, v29
	v_cvt_pk_bf16_f32 v15, v18, v19
	v_cvt_pk_bf16_f32 v16, v22, v23
	v_cvt_pk_bf16_f32 v17, v20, v21
	v_cvt_pk_bf16_f32 v18, v24, v25
	v_cvt_pk_bf16_f32 v19, v30, v31
	v_cvt_pk_bf16_f32 v20, v26, v27
	v_cvt_pk_bf16_f32 v21, v32, v33
	global_store_dwordx4 v[12:13], v[14:17], off sc1
	global_store_dwordx4 v[12:13], v[18:21], off offset:16 sc1
	v_lshl_add_u64 v[12:13], v[12:13], 0, s[6:7]
	s_cbranch_scc1 .LBB0_615

.LBB0_853:
	s_or_b64 exec, exec, s[4:5]
	v_mov_b32_e32 v217, v194
	v_mov_b32_e32 v194, v203
	v_pk_mul_f32 v[194:195], v[194:195], v[138:139] op_sel_hi:[1,0]
	v_mov_b32_e32 v229, v132
	v_pk_fma_f32 v[224:225], v[0:1], v[194:195], v[64:65]
	v_mov_b32_e32 v216, v202
	v_cvt_pk_fp8_f32 v229, v224, v225
	v_mov_b32_e32 v223, v196
	v_mov_b32_e32 v196, v199
	v_mov_b32_e32 v218, v192
	v_mov_b32_e32 v219, v190
	v_mov_b32_e32 v220, v188
	v_mov_b32_e32 v221, v186
	v_pk_mul_f32 v[216:217], v[216:217], v[138:139] op_sel_hi:[1,0]
	v_pk_mul_f32 v[196:197], v[196:197], v[138:139] op_sel_hi:[1,0]
	v_mov_b32_e32 v222, v198
	v_pk_fma_f32 v[216:217], v[4:5], v[216:217], v[68:69]
	v_pk_fma_f32 v[198:199], v[2:3], v[196:197], v[66:67]
	v_mov_b32_e32 v228, v132
	v_mov_b32_e32 v190, v193
	v_pk_mul_f32 v[192:193], v[218:219], v[138:139] op_sel_hi:[1,0]
	v_mov_b32_e32 v186, v189
	v_pk_mul_f32 v[188:189], v[220:221], v[138:139] op_sel_hi:[1,0]
	v_cvt_pk_bf16_f32 v197, v198, v199
	v_add_co_u32_e32 v226, vcc, s16, v162
	v_cvt_pk_fp8_f32 v228, v216, v217
	v_cvt_pk_fp8_f32 v229, v198, v199 op_sel:[0,0,1]
	v_pk_fma_f32 v[192:193], v[12:13], v[192:193], v[76:77]
	v_pk_fma_f32 v[188:189], v[8:9], v[188:189], v[72:73]
	v_mov_b32_e32 v198, v132
	v_mov_b32_e32 v199, v132
	v_pk_mul_f32 v[222:223], v[222:223], v[138:139] op_sel_hi:[1,0]
	v_addc_co_u32_e32 v227, vcc, 0, v163, vcc
	v_cvt_pk_fp8_f32 v198, v192, v193
	v_cvt_pk_fp8_f32 v199, v188, v189
	v_pk_fma_f32 v[222:223], v[6:7], v[222:223], v[70:71]
	v_add_co_u32_e32 v162, vcc, s18, v162
	v_cvt_pk_bf16_f32 v194, v216, v217
	v_cvt_pk_bf16_f32 v195, v222, v223
	v_cvt_pk_bf16_f32 v196, v224, v225
	v_addc_co_u32_e32 v163, vcc, 0, v163, vcc
	v_pk_mul_f32 v[190:191], v[190:191], v[138:139] op_sel_hi:[1,0]
	v_pk_mul_f32 v[186:187], v[186:187], v[138:139] op_sel_hi:[1,0]
	global_store_dwordx4 v[162:163], v[194:197], off offset:-4096 sc1
	v_cvt_pk_fp8_f32 v228, v222, v223 op_sel:[0,0,1]
	v_pk_fma_f32 v[190:191], v[14:15], v[190:191], v[78:79]
	v_pk_fma_f32 v[196:197], v[10:11], v[186:187], v[74:75]
	v_mov_b32_e32 v134, v207
	v_lshl_add_u64 v[206:207], s[58:59], 0, v[128:129]
	v_cvt_pk_fp8_f32 v198, v190, v191 op_sel:[0,0,1]
	v_cvt_pk_fp8_f32 v199, v196, v197 op_sel:[0,0,1]
	v_add_co_u32_e32 v194, vcc, s17, v206
	v_cvt_pk_bf16_f32 v186, v192, v193
	s_nop 0
	v_addc_co_u32_e32 v195, vcc, 0, v207, vcc
	v_cvt_pk_bf16_f32 v187, v190, v191
	v_cvt_pk_bf16_f32 v188, v188, v189
	v_cvt_pk_bf16_f32 v189, v196, v197
	v_pk_mul_f32 v[182:183], v[182:183], v[138:139] op_sel_hi:[1,0]
	v_pk_mul_f32 v[180:181], v[180:181], v[138:139] op_sel_hi:[1,0]
	v_pk_mul_f32 v[178:179], v[178:179], v[138:139] op_sel_hi:[1,0]
	global_store_dwordx2 v[194:195], v[228:229], off nt
	global_store_dwordx4 v[226:227], v[186:189], off offset:1024 sc1
	global_store_dwordx2 v[194:195], v[198:199], off offset:512 nt
	v_pk_fma_f32 v[182:183], v[20:21], v[182:183], v[84:85]
	v_pk_fma_f32 v[186:187], v[18:19], v[180:181], v[82:83]
	v_pk_fma_f32 v[180:181], v[16:17], v[178:179], v[80:81]
	v_mov_b32_e32 v188, v132
	v_mov_b32_e32 v189, v132
	v_cvt_pk_fp8_f32 v188, v182, v183
	v_cvt_pk_fp8_f32 v189, v180, v181
	v_pk_mul_f32 v[184:185], v[184:185], v[138:139] op_sel_hi:[1,0]
	v_mov_b32_e32 v175, v133
	v_pk_fma_f32 v[184:185], v[22:23], v[184:185], v[86:87]
	v_cvt_pk_fp8_f32 v189, v186, v187 op_sel:[0,0,1]
	v_cvt_pk_fp8_f32 v188, v184, v185 op_sel:[0,0,1]
	v_mov_b32_e32 v168, v205
	v_mov_b32_e32 v170, v173
	v_cvt_pk_bf16_f32 v178, v182, v183
	v_cvt_pk_bf16_f32 v179, v184, v185
	v_cvt_pk_bf16_f32 v180, v180, v181
	v_cvt_pk_bf16_f32 v181, v186, v187
	v_pk_mul_f32 v[174:175], v[174:175], v[138:139] op_sel_hi:[1,0]
	v_pk_mul_f32 v[170:171], v[170:171], v[138:139] op_sel_hi:[1,0]
	v_pk_mul_f32 v[168:169], v[168:169], v[138:139] op_sel_hi:[1,0]
	global_store_dwordx4 v[226:227], v[178:181], off offset:2048 sc1
	global_store_dwordx2 v[194:195], v[188:189], off offset:1024 nt
	v_pk_fma_f32 v[174:175], v[28:29], v[174:175], v[92:93]
	v_pk_fma_f32 v[172:173], v[26:27], v[170:171], v[90:91]
	v_pk_fma_f32 v[170:171], v[24:25], v[168:169], v[88:89]
	v_mov_b32_e32 v178, v132
	v_mov_b32_e32 v179, v132
	v_cvt_pk_fp8_f32 v178, v174, v175
	v_cvt_pk_fp8_f32 v179, v170, v171
	v_pk_mul_f32 v[176:177], v[176:177], v[138:139] op_sel_hi:[1,0]
	v_mov_b32_e32 v204, v200
	v_pk_fma_f32 v[176:177], v[30:31], v[176:177], v[94:95]
	v_cvt_pk_fp8_f32 v179, v172, v173 op_sel:[0,0,1]
	v_cvt_pk_fp8_f32 v178, v176, v177 op_sel:[0,0,1]
	v_mov_b32_e32 v205, v160
	v_mov_b32_e32 v160, v201
	v_cvt_pk_bf16_f32 v168, v174, v175
	v_cvt_pk_bf16_f32 v169, v176, v177
	v_cvt_pk_bf16_f32 v170, v170, v171
	v_cvt_pk_bf16_f32 v171, v172, v173
	global_store_dwordx4 v[226:227], v[168:171], off offset:3072 sc1
	global_store_dwordx2 v[194:195], v[178:179], off offset:1536 nt
	v_pk_mul_f32 v[160:161], v[160:161], v[138:139] op_sel_hi:[1,0]
	v_pk_mul_f32 v[170:171], v[204:205], v[138:139] op_sel_hi:[1,0]
	v_pk_fma_f32 v[160:161], v[32:33], v[160:161], v[96:97]
	v_pk_fma_f32 v[170:171], v[36:37], v[170:171], v[100:101]
	v_mov_b32_e32 v174, v132
	v_mov_b32_e32 v175, v132
	v_cvt_pk_fp8_f32 v174, v170, v171
	v_cvt_pk_fp8_f32 v175, v160, v161
	v_mov_b32_e32 v168, v166
	v_mov_b32_e32 v169, v164
	v_mov_b32_e32 v164, v167
	v_pk_mul_f32 v[168:169], v[168:169], v[138:139] op_sel_hi:[1,0]
	v_pk_mul_f32 v[164:165], v[164:165], v[138:139] op_sel_hi:[1,0]
	v_pk_fma_f32 v[168:169], v[38:39], v[168:169], v[102:103]
	v_pk_fma_f32 v[172:173], v[34:35], v[164:165], v[98:99]
	v_cvt_pk_fp8_f32 v174, v168, v169 op_sel:[0,0,1]
	v_cvt_pk_fp8_f32 v175, v172, v173 op_sel:[0,0,1]
	v_mov_b32_e32 v202, v150
	v_mov_b32_e32 v203, v148
	v_mov_b32_e32 v200, v146
	v_mov_b32_e32 v201, v144
	v_cvt_pk_bf16_f32 v164, v170, v171
	v_cvt_pk_bf16_f32 v165, v168, v169
	v_cvt_pk_bf16_f32 v166, v160, v161
	v_cvt_pk_bf16_f32 v167, v172, v173
	v_mov_b32_e32 v148, v151
	v_pk_mul_f32 v[150:151], v[202:203], v[138:139] op_sel_hi:[1,0]
	v_mov_b32_e32 v144, v147
	v_pk_mul_f32 v[146:147], v[200:201], v[138:139] op_sel_hi:[1,0]
	global_store_dwordx4 v[162:163], v[164:167], off sc1
	global_store_dwordx2 v[194:195], v[174:175], off offset:2048 nt
	v_pk_fma_f32 v[150:151], v[44:45], v[150:151], v[108:109]
	v_pk_fma_f32 v[146:147], v[40:41], v[146:147], v[104:105]
	v_mov_b32_e32 v164, v132
	v_mov_b32_e32 v165, v132
	v_cvt_pk_fp8_f32 v164, v150, v151
	v_cvt_pk_fp8_f32 v165, v146, v147
	v_pk_mul_f32 v[148:149], v[148:149], v[138:139] op_sel_hi:[1,0]
	v_pk_mul_f32 v[144:145], v[144:145], v[138:139] op_sel_hi:[1,0]
	v_pk_fma_f32 v[148:149], v[46:47], v[148:149], v[110:111]
	v_pk_fma_f32 v[160:161], v[42:43], v[144:145], v[106:107]
	v_cvt_pk_fp8_f32 v164, v148, v149 op_sel:[0,0,1]
	v_cvt_pk_fp8_f32 v165, v160, v161 op_sel:[0,0,1]
	v_cvt_pk_bf16_f32 v144, v150, v151
	v_cvt_pk_bf16_f32 v145, v148, v149
	v_cvt_pk_bf16_f32 v146, v146, v147
	v_cvt_pk_bf16_f32 v147, v160, v161
	global_store_dwordx4 v[162:163], v[144:147], off offset:1024 sc1
	global_store_dwordx2 v[194:195], v[164:165], off offset:2560 nt
	v_pk_mul_f32 v[150:151], v[152:153], v[138:139] op_sel_hi:[1,0]
	v_pk_mul_f32 v[144:145], v[158:159], v[138:139] op_sel_hi:[1,0]
	v_pk_mul_f32 v[146:147], v[156:157], v[138:139] op_sel_hi:[1,0]
	v_pk_fma_f32 v[148:149], v[54:55], v[144:145], v[118:119]
	v_pk_fma_f32 v[144:145], v[52:53], v[146:147], v[116:117]
	v_pk_mul_f32 v[146:147], v[154:155], v[138:139] op_sel_hi:[1,0]
	v_mov_b32_e32 v136, v139
	v_pk_fma_f32 v[152:153], v[50:51], v[146:147], v[114:115]
	v_pk_fma_f32 v[146:147], v[48:49], v[150:151], v[112:113]
	v_mov_b32_e32 v150, v132
	v_mov_b32_e32 v151, v132
	v_cvt_pk_fp8_f32 v150, v144, v145
	v_cvt_pk_fp8_f32 v151, v146, v147
	v_cvt_pk_bf16_f32 v144, v144, v145
	v_cvt_pk_bf16_f32 v145, v148, v149
	v_cvt_pk_fp8_f32 v150, v148, v149 op_sel:[0,0,1]
	v_cvt_pk_fp8_f32 v151, v152, v153 op_sel:[0,0,1]
	v_cvt_pk_bf16_f32 v146, v146, v147
	v_cvt_pk_bf16_f32 v147, v152, v153
	v_pk_mul_f32 v[140:141], v[140:141], v[138:139] op_sel_hi:[1,0]
	v_pk_mul_f32 v[136:137], v[136:137], v[138:139] op_sel_hi:[1,0]
	v_pk_mul_f32 v[134:135], v[134:135], v[138:139] op_sel_hi:[1,0]
	global_store_dwordx4 v[162:163], v[144:147], off offset:2048 sc1
	global_store_dwordx2 v[194:195], v[150:151], off offset:3072 nt
	v_pk_mul_f32 v[142:143], v[142:143], v[138:139] op_sel_hi:[1,0]
	v_pk_fma_f32 v[140:141], v[60:61], v[140:141], v[124:125]
	v_pk_fma_f32 v[138:139], v[58:59], v[136:137], v[122:123]
	v_pk_fma_f32 v[136:137], v[56:57], v[134:135], v[120:121]
	v_mov_b32_e32 v144, v132
	v_mov_b32_e32 v145, v132
	v_cvt_pk_fp8_f32 v144, v140, v141
	v_cvt_pk_fp8_f32 v145, v136, v137
	v_pk_fma_f32 v[142:143], v[62:63], v[142:143], v[126:127]
	s_add_i32 s6, s6, s8
	v_cvt_pk_fp8_f32 v144, v142, v143 op_sel:[0,0,1]
	v_cvt_pk_fp8_f32 v145, v138, v139 op_sel:[0,0,1]
	s_add_u32 s2, s2, s10
	s_addc_u32 s3, s3, s11
	v_cvt_pk_bf16_f32 v134, v140, v141
	v_cvt_pk_bf16_f32 v135, v142, v143
	v_cvt_pk_bf16_f32 v136, v136, v137
	v_cvt_pk_bf16_f32 v137, v138, v139
	v_lshl_add_u64 v[128:129], v[128:129], 0, s[12:13]
	s_cmpk_lt_i32 s6, 0x4000
	v_lshl_add_u64 v[130:131], v[130:131], 0, s[14:15]
	global_store_dwordx4 v[162:163], v[134:137], off offset:3072 sc1
	global_store_dwordx2 v[194:195], v[144:145], off offset:3584 nt
	s_cbranch_scc0 .LBB0_856
